# v10: v9 + dropped the self-max canonicalisations after the max3 trees in the attention loops
# speedup vs baseline: 1.0212x; 1.0057x over previous
; #define LAS __attribute__((address_space(3)))
; __device__ __forceinline__ float max3f(float a, float b, float c) { float r; asm("v_max3_f32 %0, %1, %2, %3" : "=v"(r) : "v"(a), "v"(b), "v"(c)); return r; }
; template <int DQK, int DV, bool BIAS> ...
;     ...
;         const LAS unsigned char* kb = lds + buf * KBUF + r32 * KP + hi * 16;
; #pragma unroll
;         for (int ks = 0; ks < NKS; ++ks) {
;             const bf16x8 k0 = *(const LAS bf16x8*)(kb + ks * 32), k1 = *(const LAS bf16x8*)(kb + 32 * KP + ks * 32);
;             if (ks == 0) { p0 = __builtin_amdgcn_mfma_f32_32x32x16_bf16(k0, qf[0], negm, 0, 0, 0); p1 = __builtin_amdgcn_mfma_f32_32x32x16_bf16(k1, qf[0], negm, 0, 0, 0); }
;             else { p0 = __builtin_amdgcn_mfma_f32_32x32x16_bf16(k0, qf[ks], p0, 0, 0, 0); p1 = __builtin_amdgcn_mfma_f32_32x32x16_bf16(k1, qf[ks], p1, 0, 0, 0); }
;         }
;         if (BIAS) {
;             asm volatile("s_nop 15\n\ts_nop 7" : "+v"(p0), "+v"(p1));
;             const float d0 = qp - (float)(t * 64 + 4 * hi);
; #pragma unroll
;             for (int r = 0; r < 16; ++r) { const float dk = d0 - (float)((r & 3) + 8 * (r >> 2)); p0[r] = p0[r] - sl2 * fabsf(dk); p1[r] = p1[r] - sl2 * fabsf(dk - 32.f); }
;         } else {
;             asm volatile("s_nop 15\n\ts_nop 7" : "+v"(p0), "+v"(p1));
;         }
;         float mxa = max3f(p0[0], p0[1], p1[0]), mxb = max3f(p0[2], p0[3], p1[1]); mxa = max3f(mxa, p1[2], p1[3]);
; #pragma unroll
;         for (int r = 4; r < 16; r += 4) { mxa = max3f(mxa, p0[r], p0[r + 1]); mxb = max3f(mxb, p0[r + 2], p0[r + 3]); mxa = max3f(mxa, p1[r], p1[r + 1]); mxb = max3f(mxb, p1[r + 2], p1[r + 3]); }
;         float mx = fmaxf(mxa, mxb);
;         if (__any(mx > 8.f)) {
.LBB0_578:
	ds_read_b128 v[82:85], v175
	ds_read_b128 v[152:155], v175 offset:32
	ds_read_b128 v[156:159], v175 offset:4608
	ds_read_b128 v[160:163], v175 offset:4640
	v_cvt_f32_u32_e32 v150, v173
	s_waitcnt lgkmcnt(3)
	v_mfma_f32_32x32x16_bf16 v[98:113], v[82:85], v[114:117], v[66:81]
	v_sub_f32_e32 v178, v172, v150
	v_add_f32_e32 v179, -1.0, v178
	s_waitcnt lgkmcnt(1)
	v_mfma_f32_32x32x16_bf16 v[82:97], v[156:159], v[114:117], v[66:81]
	v_mfma_f32_32x32x16_bf16 v[98:113], v[152:155], v[118:121], v[98:113]
	ds_read_b128 v[152:155], v175 offset:64
	ds_read_b128 v[156:159], v175 offset:96
	s_waitcnt lgkmcnt(2)
	v_mfma_f32_32x32x16_bf16 v[82:97], v[160:163], v[118:121], v[82:97]
	s_waitcnt lgkmcnt(1)
	v_mfma_f32_32x32x16_bf16 v[98:113], v[152:155], v[122:125], v[98:113]
	ds_read_b128 v[152:155], v175 offset:4672
	ds_read_b128 v[160:163], v175 offset:4704
	s_waitcnt lgkmcnt(1)
	v_mfma_f32_32x32x16_bf16 v[82:97], v[152:155], v[122:125], v[82:97]
	v_and_b32_e32 v152, 0x7fffffff, v178
	v_and_b32_e32 v153, 0x7fffffff, v179
	v_mfma_f32_32x32x16_bf16 v[98:113], v[156:159], v[126:129], v[98:113]
	s_waitcnt lgkmcnt(0)
	v_mfma_f32_32x32x16_bf16 v[82:97], v[160:163], v[126:129], v[82:97]
	s_nop 15
	s_nop 7
	s_nop 9
	v_pk_fma_f32 v[156:157], v[142:143], v[152:153], v[98:99] neg_lo:[1,0,0] neg_hi:[1,0,0]
	v_pk_add_f32 v[98:99], v[178:179], s[8:9] op_sel_hi:[1,0]
	s_nop 0
	v_fma_f32 v99, -v143, |v99|, v83
	v_fma_f32 v98, -v142, |v98|, v82
	v_pk_add_f32 v[82:83], v[178:179], s[10:11] op_sel_hi:[0,1]
	v_fma_f32 v161, -v143, |v83|, v101
	v_fma_f32 v160, -v142, |v82|, v100
	v_pk_add_f32 v[82:83], v[82:83], s[8:9] op_sel_hi:[1,0]
	v_fma_f32 v153, -v143, |v83|, v85
	v_fma_f32 v152, -v142, |v82|, v84
	v_pk_add_f32 v[82:83], v[178:179], s[22:23] op_sel_hi:[0,1]
	v_fma_f32 v165, -v143, |v83|, v103
	v_fma_f32 v164, -v142, |v82|, v102
	v_pk_add_f32 v[82:83], v[82:83], s[8:9] op_sel_hi:[1,0]
	v_fma_f32 v103, -v143, |v83|, v87
	v_fma_f32 v102, -v142, |v82|, v86
	v_pk_add_f32 v[82:83], v[178:179], s[34:35] op_sel_hi:[0,1]
	v_fma_f32 v167, -v143, |v83|, v105
	v_fma_f32 v166, -v142, |v82|, v104
	v_pk_add_f32 v[82:83], v[82:83], s[8:9] op_sel_hi:[1,0]
	v_fma_f32 v155, -v143, |v83|, v89
	v_fma_f32 v154, -v142, |v82|, v88
	v_pk_add_f32 v[82:83], v[178:179], s[36:37] op_sel_hi:[0,1]
	v_fma_f32 v159, -v143, |v83|, v107
	v_fma_f32 v158, -v142, |v82|, v106
	v_pk_add_f32 v[82:83], v[82:83], s[8:9] op_sel_hi:[1,0]
	v_fma_f32 v101, -v143, |v83|, v91
	v_fma_f32 v100, -v142, |v82|, v90
	v_pk_add_f32 v[82:83], v[178:179], s[38:39] op_sel_hi:[0,1]
	v_fma_f32 v163, -v143, |v83|, v109
	v_fma_f32 v162, -v142, |v82|, v108
	v_pk_add_f32 v[82:83], v[82:83], s[8:9] op_sel_hi:[1,0]
	v_fma_f32 v105, -v143, |v83|, v93
	v_fma_f32 v104, -v142, |v82|, v92
	v_pk_add_f32 v[82:83], v[178:179], s[40:41] op_sel_hi:[0,1]
	v_fma_f32 v111, -v143, |v83|, v111
	v_fma_f32 v110, -v142, |v82|, v110
	v_pk_add_f32 v[82:83], v[82:83], s[8:9] op_sel_hi:[1,0]
	v_fma_f32 v107, -v143, |v83|, v95
	v_fma_f32 v106, -v142, |v82|, v94
	v_pk_add_f32 v[82:83], v[178:179], s[42:43] op_sel_hi:[0,1]
	v_fma_f32 v113, -v143, |v83|, v113
	v_fma_f32 v112, -v142, |v82|, v112
	v_pk_add_f32 v[82:83], v[82:83], s[8:9] op_sel_hi:[1,0]
	v_fma_f32 v109, -v143, |v83|, v97
	v_fma_f32 v108, -v142, |v82|, v96
	v_max3_f32 v82, v156, v157, v98
	v_max3_f32 v83, v160, v161, v99
	v_max3_f32 v82, v82, v152, v153
	v_max3_f32 v83, v83, v166, v167
	v_max3_f32 v82, v82, v164, v165
	v_max3_f32 v83, v83, v154, v155
	v_max3_f32 v82, v82, v102, v103
	v_max3_f32 v83, v83, v162, v163
	v_max3_f32 v82, v82, v158, v159
	v_max3_f32 v83, v83, v104, v105
	v_max3_f32 v82, v82, v100, v101
	v_max3_f32 v83, v83, v112, v113
	v_max3_f32 v82, v82, v110, v111
	v_max3_f32 v83, v83, v108, v109
	v_max3_f32 v82, v82, v106, v107
	v_max_f32_e32 v82, v82, v83
	v_cmp_gt_f32_e32 vcc, 0xc3400000, v82
	s_cmp_eq_u64 vcc, exec
	s_cbranch_scc1 .Lsk1_p4a1
; template <int DQK, int DV, bool BIAS> ...
;     ...
;         if (__any(mx > 8.f)) {
;             mx = fmaxf(mx, __shfl_xor(mx, 32));
;             const float dl = fmaxf(mx, 0.f); mhat += dl;
;             const float f = __builtin_amdgcn_exp2f(-dl);
; #pragma unroll
;             for (int r = 0; r < 16; ++r) { p0[r] -= dl; p1[r] -= dl; negm[r] = -mhat; }
;             l *= f;
; #pragma unroll
;             for (int d = 0; d < NDT; ++d)
; #pragma unroll
;                 for (int r = 0; r < 16; ++r) o[d][r] *= f;
;         }
	v_cmp_lt_f32_e32 vcc, s52, v82
	s_cbranch_vccz .LBB0_580
	v_and_b32_e32 v67, 64, v170
	v_xor_b32_e32 v66, 32, v170
	v_add_u32_e32 v67, 64, v67
	v_cmp_lt_i32_e32 vcc, v66, v67
	s_nop 1
	v_cndmask_b32_e32 v66, v170, v66, vcc
	v_lshlrev_b32_e32 v66, 2, v66
	ds_bpermute_b32 v66, v66, v82
	s_waitcnt lgkmcnt(0)
	v_max3_f32 v67, v82, v66, 0
	v_exp_f32_e64 v66, -v67
	v_add_f32_e32 v176, v176, v67
	v_xor_b32_e32 v82, 0x80000000, v176
	v_sub_f32_e32 v98, v98, v67
	v_sub_f32_e32 v99, v99, v67
	v_sub_f32_e32 v152, v152, v67
	v_sub_f32_e32 v153, v153, v67
	v_sub_f32_e32 v102, v102, v67
	v_sub_f32_e32 v103, v103, v67
	v_sub_f32_e32 v154, v154, v67
	v_sub_f32_e32 v155, v155, v67
	v_sub_f32_e32 v100, v100, v67
	v_sub_f32_e32 v101, v101, v67
	v_sub_f32_e32 v104, v104, v67
	v_sub_f32_e32 v105, v105, v67
	v_sub_f32_e32 v106, v106, v67
	v_sub_f32_e32 v107, v107, v67
	v_sub_f32_e32 v108, v108, v67
	v_sub_f32_e32 v109, v109, v67
	v_pk_mul_f32 v[64:65], v[64:65], v[66:67] op_sel_hi:[1,0]
	v_pk_mul_f32 v[62:63], v[62:63], v[66:67] op_sel_hi:[1,0]
	v_pk_mul_f32 v[60:61], v[60:61], v[66:67] op_sel_hi:[1,0]
	v_pk_mul_f32 v[58:59], v[58:59], v[66:67] op_sel_hi:[1,0]
	v_pk_mul_f32 v[56:57], v[56:57], v[66:67] op_sel_hi:[1,0]
	v_pk_mul_f32 v[54:55], v[54:55], v[66:67] op_sel_hi:[1,0]
	v_pk_mul_f32 v[52:53], v[52:53], v[66:67] op_sel_hi:[1,0]
	v_pk_mul_f32 v[50:51], v[50:51], v[66:67] op_sel_hi:[1,0]
	v_pk_mul_f32 v[48:49], v[48:49], v[66:67] op_sel_hi:[1,0]
	v_pk_mul_f32 v[46:47], v[46:47], v[66:67] op_sel_hi:[1,0]
	v_pk_mul_f32 v[44:45], v[44:45], v[66:67] op_sel_hi:[1,0]
	v_pk_mul_f32 v[42:43], v[42:43], v[66:67] op_sel_hi:[1,0]
	v_pk_mul_f32 v[40:41], v[40:41], v[66:67] op_sel_hi:[1,0]
	v_pk_mul_f32 v[38:39], v[38:39], v[66:67] op_sel_hi:[1,0]
	v_pk_mul_f32 v[36:37], v[36:37], v[66:67] op_sel_hi:[1,0]
	v_pk_mul_f32 v[34:35], v[34:35], v[66:67] op_sel_hi:[1,0]
	v_pk_mul_f32 v[32:33], v[32:33], v[66:67] op_sel_hi:[1,0]
	v_pk_mul_f32 v[30:31], v[30:31], v[66:67] op_sel_hi:[1,0]
	v_pk_mul_f32 v[28:29], v[28:29], v[66:67] op_sel_hi:[1,0]
	v_pk_mul_f32 v[26:27], v[26:27], v[66:67] op_sel_hi:[1,0]
	v_pk_mul_f32 v[24:25], v[24:25], v[66:67] op_sel_hi:[1,0]
	v_pk_mul_f32 v[22:23], v[22:23], v[66:67] op_sel_hi:[1,0]
	v_pk_mul_f32 v[20:21], v[20:21], v[66:67] op_sel_hi:[1,0]
	v_pk_mul_f32 v[18:19], v[18:19], v[66:67] op_sel_hi:[1,0]
	v_pk_mul_f32 v[16:17], v[16:17], v[66:67] op_sel_hi:[1,0]
	v_pk_mul_f32 v[14:15], v[14:15], v[66:67] op_sel_hi:[1,0]
	v_pk_mul_f32 v[12:13], v[12:13], v[66:67] op_sel_hi:[1,0]
	v_pk_mul_f32 v[10:11], v[10:11], v[66:67] op_sel_hi:[1,0]
	v_pk_mul_f32 v[8:9], v[8:9], v[66:67] op_sel_hi:[1,0]
	v_pk_mul_f32 v[6:7], v[6:7], v[66:67] op_sel_hi:[1,0]
	v_pk_mul_f32 v[4:5], v[4:5], v[66:67] op_sel_hi:[1,0]
	v_pk_mul_f32 v[2:3], v[2:3], v[66:67] op_sel_hi:[1,0]
	v_sub_f32_e32 v156, v156, v67
	v_sub_f32_e32 v157, v157, v67
	v_sub_f32_e32 v160, v160, v67
	v_sub_f32_e32 v161, v161, v67
	v_sub_f32_e32 v164, v164, v67
	v_sub_f32_e32 v165, v165, v67
	v_sub_f32_e32 v166, v166, v67
	v_sub_f32_e32 v167, v167, v67
	v_sub_f32_e32 v158, v158, v67
	v_sub_f32_e32 v159, v159, v67
	v_sub_f32_e32 v162, v162, v67
	v_sub_f32_e32 v163, v163, v67
	v_sub_f32_e32 v110, v110, v67
	v_sub_f32_e32 v111, v111, v67
	v_sub_f32_e32 v112, v112, v67
	v_sub_f32_e32 v113, v113, v67
	v_mul_f32_e32 v151, v151, v66
	v_mov_b32_e32 v66, v82
	v_mov_b32_e32 v67, v82
	v_mov_b32_e32 v68, v82
	v_mov_b32_e32 v69, v82
	v_mov_b32_e32 v70, v82
	v_mov_b32_e32 v71, v82
	v_mov_b32_e32 v72, v82
	v_mov_b32_e32 v73, v82
	v_mov_b32_e32 v74, v82
	v_mov_b32_e32 v75, v82
	v_mov_b32_e32 v76, v82
	v_mov_b32_e32 v77, v82
	v_mov_b32_e32 v78, v82
	v_mov_b32_e32 v79, v82
	v_mov_b32_e32 v80, v82
	v_mov_b32_e32 v81, v82
	s_branch .LBB0_581

; #define LAS __attribute__((address_space(3)))
; __device__ __forceinline__ float max3f(float a, float b, float c) { float r; asm("v_max3_f32 %0, %1, %2, %3" : "=v"(r) : "v"(a), "v"(b), "v"(c)); return r; }
; template <int DQK, int DV, bool BIAS> ...
;     ...
;         const LAS unsigned char* kb = lds + buf * KBUF + r32 * KP + hi * 16;
; #pragma unroll
;         for (int ks = 0; ks < NKS; ++ks) {
;             const bf16x8 k0 = *(const LAS bf16x8*)(kb + ks * 32), k1 = *(const LAS bf16x8*)(kb + 32 * KP + ks * 32);
;             if (ks == 0) { p0 = __builtin_amdgcn_mfma_f32_32x32x16_bf16(k0, qf[0], negm, 0, 0, 0); p1 = __builtin_amdgcn_mfma_f32_32x32x16_bf16(k1, qf[0], negm, 0, 0, 0); }
;             else { p0 = __builtin_amdgcn_mfma_f32_32x32x16_bf16(k0, qf[ks], p0, 0, 0, 0); p1 = __builtin_amdgcn_mfma_f32_32x32x16_bf16(k1, qf[ks], p1, 0, 0, 0); }
;         }
;         if (BIAS) {
;             asm volatile("s_nop 15\n\ts_nop 7" : "+v"(p0), "+v"(p1));
;             const float d0 = qp - (float)(t * 64 + 4 * hi);
; #pragma unroll
;             for (int r = 0; r < 16; ++r) { const float dk = d0 - (float)((r & 3) + 8 * (r >> 2)); p0[r] = p0[r] - sl2 * fabsf(dk); p1[r] = p1[r] - sl2 * fabsf(dk - 32.f); }
;         } else {
;             asm volatile("s_nop 15\n\ts_nop 7" : "+v"(p0), "+v"(p1));
;         }
;         float mxa = max3f(p0[0], p0[1], p1[0]), mxb = max3f(p0[2], p0[3], p1[1]); mxa = max3f(mxa, p1[2], p1[3]);
; #pragma unroll
;         for (int r = 4; r < 16; r += 4) { mxa = max3f(mxa, p0[r], p0[r + 1]); mxb = max3f(mxb, p0[r + 2], p0[r + 3]); mxa = max3f(mxa, p1[r], p1[r + 1]); mxb = max3f(mxb, p1[r + 2], p1[r + 3]); }
;         float mx = fmaxf(mxa, mxb);
;         if (__any(mx > 8.f)) {
.LBB0_584:
	ds_read_b128 v[192:195], v175 offset:9216
	ds_read_b128 v[196:199], v175 offset:9248
	v_add_f32_e32 v156, 0, v156
	v_add_f32_e32 v156, v157, v156
	v_add_f32_e32 v156, v160, v156
	s_waitcnt lgkmcnt(1)
	v_mfma_f32_32x32x16_bf16 v[98:113], v[192:195], v[114:117], v[66:81]
	ds_read_b128 v[192:195], v175 offset:13824
	ds_read_b128 v[200:203], v175 offset:13856
	v_add_f32_e32 v156, v161, v156
	v_add_f32_e32 v156, v164, v156
	v_add_f32_e32 v150, v150, v156
	v_add_f32_e32 v150, v165, v150
	v_add_f32_e32 v150, v166, v150
	v_add_f32_e32 v150, v167, v150
	s_waitcnt lgkmcnt(1)
	v_mfma_f32_32x32x16_bf16 v[82:97], v[192:195], v[114:117], v[66:81]
	v_add_f32_e32 v150, v177, v150
	v_add_f32_e32 v150, v178, v150
	v_add_f32_e32 v150, v158, v150
	v_add_f32_e32 v150, v159, v150
	ds_read_b128 v[164:167], v175 offset:9280
	v_add_f32_e32 v150, v162, v150
	v_add_f32_e32 v150, v163, v150
	v_mfma_f32_32x32x16_bf16 v[98:113], v[196:199], v[118:121], v[98:113]
	v_add_f32_e32 v150, v179, v150
	v_add_f32_e32 v150, v180, v150
	v_add_f32_e32 v150, v181, v150
	v_add_f32_e32 v150, v152, v150
	ds_read_b128 v[156:159], v175 offset:13888
	ds_read_b128 v[160:163], v175 offset:9312
	v_add_f32_e32 v150, v153, v150
	v_add_f32_e32 v150, v182, v150
	s_waitcnt lgkmcnt(3)
	v_mfma_f32_32x32x16_bf16 v[82:97], v[200:203], v[118:121], v[82:97]
	v_add_f32_e32 v150, v183, v150
	v_add_f32_e32 v150, v154, v150
	v_add_f32_e32 v150, v155, v150
	v_add_f32_e32 v150, v184, v150
	v_add_f32_e32 v150, v185, v150
	v_add_u32_e32 v152, 64, v173
	v_add_f32_e32 v150, v186, v150
	s_waitcnt lgkmcnt(2)
	v_mfma_f32_32x32x16_bf16 v[98:113], v[164:167], v[122:125], v[98:113]
	ds_read_b128 v[164:167], v175 offset:13920
	v_cvt_f32_u32_e32 v152, v152
	v_add_f32_e32 v150, v187, v150
	v_add_f32_e32 v150, v188, v150
	v_add_f32_e32 v150, v191, v150
	v_add_f32_e32 v150, v189, v150
	v_add_f32_e32 v150, v190, v150
	s_waitcnt lgkmcnt(2)
	v_mfma_f32_32x32x16_bf16 v[82:97], v[156:159], v[122:125], v[82:97]
	v_add_f32_e32 v158, v151, v150
	s_waitcnt lgkmcnt(1)
	v_mfma_f32_32x32x16_bf16 v[98:113], v[160:163], v[126:129], v[98:113]
	v_sub_f32_e32 v160, v172, v152
	v_add_f32_e32 v161, -1.0, v160
	v_and_b32_e32 v150, 0x7fffffff, v160
	v_and_b32_e32 v151, 0x7fffffff, v161
	s_waitcnt lgkmcnt(0)
	v_mfma_f32_32x32x16_bf16 v[82:97], v[164:167], v[126:129], v[82:97]
	s_nop 15
	s_nop 7
	s_nop 5
	v_pk_fma_f32 v[150:151], v[142:143], v[150:151], v[98:99] neg_lo:[1,0,0] neg_hi:[1,0,0]
	v_pk_add_f32 v[98:99], v[160:161], s[8:9] op_sel_hi:[1,0]
	s_nop 0
	v_fma_f32 v83, -v143, |v99|, v83
	v_fma_f32 v82, -v142, |v98|, v82
	s_nop 0
	v_pk_add_f32 v[98:99], v[160:161], s[10:11] op_sel_hi:[0,1]
	v_fma_f32 v153, -v143, |v99|, v101
	v_fma_f32 v152, -v142, |v98|, v100
	v_pk_add_f32 v[98:99], v[98:99], s[8:9] op_sel_hi:[1,0]
	v_fma_f32 v99, -v143, |v99|, v85
	v_fma_f32 v98, -v142, |v98|, v84
	v_pk_add_f32 v[84:85], v[160:161], s[22:23] op_sel_hi:[0,1]
	v_fma_f32 v155, -v143, |v85|, v103
	v_fma_f32 v154, -v142, |v84|, v102
	v_pk_add_f32 v[84:85], v[84:85], s[8:9] op_sel_hi:[1,0]
	v_fma_f32 v101, -v143, |v85|, v87
	v_fma_f32 v100, -v142, |v84|, v86
	v_pk_add_f32 v[84:85], v[160:161], s[34:35] op_sel_hi:[0,1]
	v_fma_f32 v157, -v143, |v85|, v105
	v_fma_f32 v156, -v142, |v84|, v104
	v_pk_add_f32 v[84:85], v[84:85], s[8:9] op_sel_hi:[1,0]
	v_fma_f32 v103, -v143, |v85|, v89
	v_fma_f32 v102, -v142, |v84|, v88
	v_pk_add_f32 v[84:85], v[160:161], s[36:37] op_sel_hi:[0,1]
	v_fma_f32 v105, -v143, |v85|, v107
	v_fma_f32 v104, -v142, |v84|, v106
	v_pk_add_f32 v[86:87], v[160:161], s[38:39] op_sel_hi:[0,1]
	v_pk_add_f32 v[84:85], v[84:85], s[8:9] op_sel_hi:[1,0]
	v_fma_f32 v107, -v143, |v87|, v109
	v_fma_f32 v106, -v142, |v86|, v108
	v_fma_f32 v85, -v143, |v85|, v91
	v_fma_f32 v84, -v142, |v84|, v90
	v_pk_add_f32 v[86:87], v[86:87], s[8:9] op_sel_hi:[1,0]
	v_pk_add_f32 v[88:89], v[160:161], s[40:41] op_sel_hi:[0,1]
	v_fma_f32 v87, -v143, |v87|, v93
	v_fma_f32 v86, -v142, |v86|, v92
	v_fma_f32 v93, -v143, |v89|, v111
	v_fma_f32 v92, -v142, |v88|, v110
	v_pk_add_f32 v[88:89], v[88:89], s[8:9] op_sel_hi:[1,0]
	v_fma_f32 v89, -v143, |v89|, v95
	v_fma_f32 v88, -v142, |v88|, v94
	v_pk_add_f32 v[90:91], v[160:161], s[42:43] op_sel_hi:[0,1]
	v_fma_f32 v95, -v143, |v91|, v113
	v_fma_f32 v94, -v142, |v90|, v112
	v_pk_add_f32 v[90:91], v[90:91], s[8:9] op_sel_hi:[1,0]
	v_fma_f32 v91, -v143, |v91|, v97
	v_fma_f32 v90, -v142, |v90|, v96
	v_max3_f32 v96, v150, v151, v82
	v_max3_f32 v97, v152, v153, v83
	v_max3_f32 v96, v96, v98, v99
	v_max3_f32 v97, v97, v156, v157
	v_max3_f32 v96, v96, v154, v155
	v_max3_f32 v97, v97, v102, v103
	v_max3_f32 v96, v96, v100, v101
	v_max3_f32 v97, v97, v106, v107
	v_max3_f32 v96, v96, v104, v105
	v_max3_f32 v97, v97, v86, v87
	v_max3_f32 v96, v96, v84, v85
	v_max3_f32 v97, v97, v94, v95
	v_max3_f32 v96, v96, v92, v93
	v_max3_f32 v97, v97, v90, v91
	v_max3_f32 v96, v96, v88, v89
	v_max_f32_e32 v96, v96, v97
	v_cmp_gt_f32_e32 vcc, 0xc3400000, v96
	s_cmp_eq_u64 vcc, exec
	s_cbranch_scc1 .Lsk2_p4a1
; template <int DQK, int DV, bool BIAS> ...
;     ...
;         if (__any(mx > 8.f)) {
;             mx = fmaxf(mx, __shfl_xor(mx, 32));
;             const float dl = fmaxf(mx, 0.f); mhat += dl;
;             const float f = __builtin_amdgcn_exp2f(-dl);
; #pragma unroll
;             for (int r = 0; r < 16; ++r) { p0[r] -= dl; p1[r] -= dl; negm[r] = -mhat; }
;             l *= f;
; #pragma unroll
;             for (int d = 0; d < NDT; ++d)
; #pragma unroll
;                 for (int r = 0; r < 16; ++r) o[d][r] *= f;
;         }
	v_cmp_lt_f32_e32 vcc, s52, v96
	s_cbranch_vccz .LBB0_575
	v_and_b32_e32 v67, 64, v170
	v_xor_b32_e32 v66, 32, v170
	v_add_u32_e32 v67, 64, v67
	v_cmp_lt_i32_e32 vcc, v66, v67
	s_nop 1
	v_cndmask_b32_e32 v66, v170, v66, vcc
	v_lshlrev_b32_e32 v66, 2, v66
	ds_bpermute_b32 v66, v66, v96
	s_waitcnt lgkmcnt(0)
	v_max3_f32 v67, v96, v66, 0
	v_exp_f32_e64 v68, -v67
	v_add_f32_e32 v176, v176, v67
	v_xor_b32_e32 v66, 0x80000000, v176
	v_sub_f32_e32 v82, v82, v67
	v_sub_f32_e32 v83, v83, v67
	v_sub_f32_e32 v98, v98, v67
	v_sub_f32_e32 v99, v99, v67
	v_sub_f32_e32 v100, v100, v67
	v_sub_f32_e32 v101, v101, v67
	v_sub_f32_e32 v102, v102, v67
	v_sub_f32_e32 v103, v103, v67
	v_sub_f32_e32 v84, v84, v67
	v_sub_f32_e32 v85, v85, v67
	v_sub_f32_e32 v86, v86, v67
	v_sub_f32_e32 v87, v87, v67
	v_sub_f32_e32 v88, v88, v67
	v_sub_f32_e32 v89, v89, v67
	v_sub_f32_e32 v90, v90, v67
	v_sub_f32_e32 v91, v91, v67
	v_pk_mul_f32 v[64:65], v[64:65], v[68:69] op_sel_hi:[1,0]
	v_pk_mul_f32 v[62:63], v[62:63], v[68:69] op_sel_hi:[1,0]
	v_pk_mul_f32 v[60:61], v[60:61], v[68:69] op_sel_hi:[1,0]
	v_pk_mul_f32 v[58:59], v[58:59], v[68:69] op_sel_hi:[1,0]
	v_pk_mul_f32 v[56:57], v[56:57], v[68:69] op_sel_hi:[1,0]
	v_pk_mul_f32 v[54:55], v[54:55], v[68:69] op_sel_hi:[1,0]
	v_pk_mul_f32 v[52:53], v[52:53], v[68:69] op_sel_hi:[1,0]
	v_pk_mul_f32 v[50:51], v[50:51], v[68:69] op_sel_hi:[1,0]
	v_pk_mul_f32 v[48:49], v[48:49], v[68:69] op_sel_hi:[1,0]
	v_pk_mul_f32 v[46:47], v[46:47], v[68:69] op_sel_hi:[1,0]
	v_pk_mul_f32 v[44:45], v[44:45], v[68:69] op_sel_hi:[1,0]
	v_pk_mul_f32 v[42:43], v[42:43], v[68:69] op_sel_hi:[1,0]
	v_pk_mul_f32 v[40:41], v[40:41], v[68:69] op_sel_hi:[1,0]
	v_pk_mul_f32 v[38:39], v[38:39], v[68:69] op_sel_hi:[1,0]
	v_pk_mul_f32 v[36:37], v[36:37], v[68:69] op_sel_hi:[1,0]
	v_pk_mul_f32 v[34:35], v[34:35], v[68:69] op_sel_hi:[1,0]
	v_pk_mul_f32 v[32:33], v[32:33], v[68:69] op_sel_hi:[1,0]
	v_pk_mul_f32 v[30:31], v[30:31], v[68:69] op_sel_hi:[1,0]
	v_pk_mul_f32 v[28:29], v[28:29], v[68:69] op_sel_hi:[1,0]
	v_pk_mul_f32 v[26:27], v[26:27], v[68:69] op_sel_hi:[1,0]
	v_pk_mul_f32 v[24:25], v[24:25], v[68:69] op_sel_hi:[1,0]
	v_pk_mul_f32 v[22:23], v[22:23], v[68:69] op_sel_hi:[1,0]
	v_pk_mul_f32 v[20:21], v[20:21], v[68:69] op_sel_hi:[1,0]
	v_pk_mul_f32 v[18:19], v[18:19], v[68:69] op_sel_hi:[1,0]
	v_pk_mul_f32 v[16:17], v[16:17], v[68:69] op_sel_hi:[1,0]
	v_pk_mul_f32 v[14:15], v[14:15], v[68:69] op_sel_hi:[1,0]
	v_pk_mul_f32 v[12:13], v[12:13], v[68:69] op_sel_hi:[1,0]
	v_pk_mul_f32 v[10:11], v[10:11], v[68:69] op_sel_hi:[1,0]
	v_pk_mul_f32 v[8:9], v[8:9], v[68:69] op_sel_hi:[1,0]
	v_pk_mul_f32 v[6:7], v[6:7], v[68:69] op_sel_hi:[1,0]
	v_pk_mul_f32 v[4:5], v[4:5], v[68:69] op_sel_hi:[1,0]
	v_pk_mul_f32 v[2:3], v[2:3], v[68:69] op_sel_hi:[1,0]
	v_sub_f32_e32 v150, v150, v67
	v_sub_f32_e32 v151, v151, v67
	v_sub_f32_e32 v152, v152, v67
	v_sub_f32_e32 v153, v153, v67
	v_sub_f32_e32 v154, v154, v67
	v_sub_f32_e32 v155, v155, v67
	v_sub_f32_e32 v156, v156, v67
	v_sub_f32_e32 v157, v157, v67
	v_sub_f32_e32 v104, v104, v67
	v_sub_f32_e32 v105, v105, v67
	v_sub_f32_e32 v106, v106, v67
	v_sub_f32_e32 v107, v107, v67
	v_sub_f32_e32 v92, v92, v67
	v_sub_f32_e32 v93, v93, v67
	v_sub_f32_e32 v94, v94, v67
	v_sub_f32_e32 v95, v95, v67
	v_mul_f32_e32 v158, v158, v68
	v_mov_b32_e32 v67, v66
	v_mov_b32_e32 v68, v66
	v_mov_b32_e32 v69, v66
	v_mov_b32_e32 v70, v66
	v_mov_b32_e32 v71, v66
	v_mov_b32_e32 v72, v66
	v_mov_b32_e32 v73, v66
	v_mov_b32_e32 v74, v66
	v_mov_b32_e32 v75, v66
	v_mov_b32_e32 v76, v66
	v_mov_b32_e32 v77, v66
	v_mov_b32_e32 v78, v66
	v_mov_b32_e32 v79, v66
	v_mov_b32_e32 v80, v66
	v_mov_b32_e32 v81, v66
	s_branch .LBB0_575

; #define LAS __attribute__((address_space(3)))
; __device__ __forceinline__ float max3f(float a, float b, float c) { float r; asm("v_max3_f32 %0, %1, %2, %3" : "=v"(r) : "v"(a), "v"(b), "v"(c)); return r; }
; template <int DQK, int DV, bool BIAS> ...
;     ...
;         const LAS unsigned char* kb = lds + buf * KBUF + r32 * KP + hi * 16;
; #pragma unroll
;         for (int ks = 0; ks < NKS; ++ks) {
;             const bf16x8 k0 = *(const LAS bf16x8*)(kb + ks * 32), k1 = *(const LAS bf16x8*)(kb + 32 * KP + ks * 32);
;             if (ks == 0) { p0 = __builtin_amdgcn_mfma_f32_32x32x16_bf16(k0, qf[0], negm, 0, 0, 0); p1 = __builtin_amdgcn_mfma_f32_32x32x16_bf16(k1, qf[0], negm, 0, 0, 0); }
;             else { p0 = __builtin_amdgcn_mfma_f32_32x32x16_bf16(k0, qf[ks], p0, 0, 0, 0); p1 = __builtin_amdgcn_mfma_f32_32x32x16_bf16(k1, qf[ks], p1, 0, 0, 0); }
;         }
;         if (BIAS) {
;             asm volatile("s_nop 15\n\ts_nop 7" : "+v"(p0), "+v"(p1));
;             const float d0 = qp - (float)(t * 64 + 4 * hi);
; #pragma unroll
;             for (int r = 0; r < 16; ++r) { const float dk = d0 - (float)((r & 3) + 8 * (r >> 2)); p0[r] = p0[r] - sl2 * fabsf(dk); p1[r] = p1[r] - sl2 * fabsf(dk - 32.f); }
;         } else {
;             asm volatile("s_nop 15\n\ts_nop 7" : "+v"(p0), "+v"(p1));
;         }
;         float mxa = max3f(p0[0], p0[1], p1[0]), mxb = max3f(p0[2], p0[3], p1[1]); mxa = max3f(mxa, p1[2], p1[3]);
; #pragma unroll
;         for (int r = 4; r < 16; r += 4) { mxa = max3f(mxa, p0[r], p0[r + 1]); mxb = max3f(mxb, p0[r + 2], p0[r + 3]); mxa = max3f(mxa, p1[r], p1[r + 1]); mxb = max3f(mxb, p1[r + 2], p1[r + 3]); }
;         float mx = fmaxf(mxa, mxb);
;         if (__any(mx > 8.f)) {
.LBB0_590:
	ds_read_b128 v[82:85], v179
	ds_read_b128 v[152:155], v179 offset:32
	ds_read_b128 v[156:159], v179 offset:4608
	ds_read_b128 v[160:163], v179 offset:4640
	v_cvt_f32_u32_e32 v150, v177
	s_waitcnt lgkmcnt(3)
	v_mfma_f32_32x32x16_bf16 v[98:113], v[82:85], v[114:117], v[66:81]
	v_sub_f32_e32 v182, v176, v150
	v_add_f32_e32 v183, -1.0, v182
	s_waitcnt lgkmcnt(1)
	v_mfma_f32_32x32x16_bf16 v[82:97], v[156:159], v[114:117], v[66:81]
	v_mfma_f32_32x32x16_bf16 v[98:113], v[152:155], v[118:121], v[98:113]
	ds_read_b128 v[152:155], v179 offset:64
	ds_read_b128 v[156:159], v179 offset:96
	s_waitcnt lgkmcnt(2)
	v_mfma_f32_32x32x16_bf16 v[82:97], v[160:163], v[118:121], v[82:97]
	s_waitcnt lgkmcnt(1)
	v_mfma_f32_32x32x16_bf16 v[98:113], v[152:155], v[122:125], v[98:113]
	ds_read_b128 v[152:155], v179 offset:4672
	ds_read_b128 v[160:163], v179 offset:4704
	s_waitcnt lgkmcnt(1)
	v_mfma_f32_32x32x16_bf16 v[82:97], v[152:155], v[122:125], v[82:97]
	v_and_b32_e32 v152, 0x7fffffff, v182
	v_and_b32_e32 v153, 0x7fffffff, v183
	v_mfma_f32_32x32x16_bf16 v[98:113], v[156:159], v[126:129], v[98:113]
	s_waitcnt lgkmcnt(0)
	v_mfma_f32_32x32x16_bf16 v[82:97], v[160:163], v[126:129], v[82:97]
	s_nop 15
	s_nop 7
	s_nop 9
	v_pk_fma_f32 v[156:157], v[142:143], v[152:153], v[98:99] neg_lo:[1,0,0] neg_hi:[1,0,0]
	v_pk_add_f32 v[98:99], v[182:183], s[6:7] op_sel_hi:[1,0]
	s_nop 0
	v_fma_f32 v99, -v143, |v99|, v83
	v_fma_f32 v98, -v142, |v98|, v82
	v_pk_add_f32 v[82:83], v[182:183], s[8:9] op_sel_hi:[0,1]
	v_fma_f32 v161, -v143, |v83|, v101
	v_fma_f32 v160, -v142, |v82|, v100
	v_pk_add_f32 v[82:83], v[82:83], s[6:7] op_sel_hi:[1,0]
	v_fma_f32 v153, -v143, |v83|, v85
	v_fma_f32 v152, -v142, |v82|, v84
	v_pk_add_f32 v[82:83], v[182:183], s[10:11] op_sel_hi:[0,1]
	v_fma_f32 v165, -v143, |v83|, v103
	v_fma_f32 v164, -v142, |v82|, v102
	v_pk_add_f32 v[82:83], v[82:83], s[6:7] op_sel_hi:[1,0]
	v_fma_f32 v103, -v143, |v83|, v87
	v_fma_f32 v102, -v142, |v82|, v86
	v_pk_add_f32 v[82:83], v[182:183], s[22:23] op_sel_hi:[0,1]
	v_fma_f32 v167, -v143, |v83|, v105
	v_fma_f32 v166, -v142, |v82|, v104
	v_pk_add_f32 v[82:83], v[82:83], s[6:7] op_sel_hi:[1,0]
	v_fma_f32 v155, -v143, |v83|, v89
	v_fma_f32 v154, -v142, |v82|, v88
	v_pk_add_f32 v[82:83], v[182:183], s[34:35] op_sel_hi:[0,1]
	v_fma_f32 v159, -v143, |v83|, v107
	v_fma_f32 v158, -v142, |v82|, v106
	v_pk_add_f32 v[82:83], v[82:83], s[6:7] op_sel_hi:[1,0]
	v_fma_f32 v101, -v143, |v83|, v91
	v_fma_f32 v100, -v142, |v82|, v90
	v_pk_add_f32 v[82:83], v[182:183], s[36:37] op_sel_hi:[0,1]
	v_fma_f32 v163, -v143, |v83|, v109
	v_fma_f32 v162, -v142, |v82|, v108
	v_pk_add_f32 v[82:83], v[82:83], s[6:7] op_sel_hi:[1,0]
	v_fma_f32 v105, -v143, |v83|, v93
	v_fma_f32 v104, -v142, |v82|, v92
	v_pk_add_f32 v[82:83], v[182:183], s[38:39] op_sel_hi:[0,1]
	v_fma_f32 v111, -v143, |v83|, v111
	v_fma_f32 v110, -v142, |v82|, v110
	v_pk_add_f32 v[82:83], v[82:83], s[6:7] op_sel_hi:[1,0]
	v_fma_f32 v107, -v143, |v83|, v95
	v_fma_f32 v106, -v142, |v82|, v94
	v_pk_add_f32 v[82:83], v[182:183], s[40:41] op_sel_hi:[0,1]
	v_fma_f32 v113, -v143, |v83|, v113
	v_fma_f32 v112, -v142, |v82|, v112
	v_pk_add_f32 v[82:83], v[82:83], s[6:7] op_sel_hi:[1,0]
	v_fma_f32 v109, -v143, |v83|, v97
	v_fma_f32 v108, -v142, |v82|, v96
	v_max3_f32 v82, v156, v157, v98
	v_max3_f32 v83, v160, v161, v99
	v_max3_f32 v82, v82, v152, v153
	v_max3_f32 v83, v83, v166, v167
	v_max3_f32 v82, v82, v164, v165
	v_max3_f32 v83, v83, v154, v155
	v_max3_f32 v82, v82, v102, v103
	v_max3_f32 v83, v83, v162, v163
	v_max3_f32 v82, v82, v158, v159
	v_max3_f32 v83, v83, v104, v105
	v_max3_f32 v82, v82, v100, v101
	v_max3_f32 v83, v83, v112, v113
	v_max3_f32 v82, v82, v110, v111
	v_max3_f32 v83, v83, v108, v109
	v_max3_f32 v82, v82, v106, v107
	v_max_f32_e32 v82, v82, v83
	v_cmp_gt_f32_e32 vcc, 0xc3400000, v82
	s_cmp_eq_u64 vcc, exec
	s_cbranch_scc1 .Lsk1_p4a2
; template <int DQK, int DV, bool BIAS> ...
;     ...
;         if (__any(mx > 8.f)) {
;             mx = fmaxf(mx, __shfl_xor(mx, 32));
;             const float dl = fmaxf(mx, 0.f); mhat += dl;
;             const float f = __builtin_amdgcn_exp2f(-dl);
; #pragma unroll
;             for (int r = 0; r < 16; ++r) { p0[r] -= dl; p1[r] -= dl; negm[r] = -mhat; }
;             l *= f;
; #pragma unroll
;             for (int d = 0; d < NDT; ++d)
; #pragma unroll
;                 for (int r = 0; r < 16; ++r) o[d][r] *= f;
;         }
	v_cmp_lt_f32_e32 vcc, s44, v82
	s_cbranch_vccz .LBB0_592
	ds_bpermute_b32 v66, v168, v82
	s_waitcnt lgkmcnt(0)
	v_max3_f32 v67, v82, v66, 0
	v_exp_f32_e64 v66, -v67
	v_add_f32_e32 v180, v180, v67
	v_xor_b32_e32 v82, 0x80000000, v180
	v_sub_f32_e32 v98, v98, v67
	v_sub_f32_e32 v99, v99, v67
	v_sub_f32_e32 v152, v152, v67
	v_sub_f32_e32 v153, v153, v67
	v_sub_f32_e32 v102, v102, v67
	v_sub_f32_e32 v103, v103, v67
	v_sub_f32_e32 v154, v154, v67
	v_sub_f32_e32 v155, v155, v67
	v_sub_f32_e32 v100, v100, v67
	v_sub_f32_e32 v101, v101, v67
	v_sub_f32_e32 v104, v104, v67
	v_sub_f32_e32 v105, v105, v67
	v_sub_f32_e32 v106, v106, v67
	v_sub_f32_e32 v107, v107, v67
	v_sub_f32_e32 v108, v108, v67
	v_sub_f32_e32 v109, v109, v67
	v_pk_mul_f32 v[16:17], v[16:17], v[66:67] op_sel_hi:[1,0]
	v_pk_mul_f32 v[14:15], v[14:15], v[66:67] op_sel_hi:[1,0]
	v_pk_mul_f32 v[12:13], v[12:13], v[66:67] op_sel_hi:[1,0]
	v_pk_mul_f32 v[10:11], v[10:11], v[66:67] op_sel_hi:[1,0]
	v_pk_mul_f32 v[8:9], v[8:9], v[66:67] op_sel_hi:[1,0]
	v_pk_mul_f32 v[6:7], v[6:7], v[66:67] op_sel_hi:[1,0]
	v_pk_mul_f32 v[4:5], v[4:5], v[66:67] op_sel_hi:[1,0]
	v_pk_mul_f32 v[2:3], v[2:3], v[66:67] op_sel_hi:[1,0]
	v_pk_mul_f32 v[32:33], v[32:33], v[66:67] op_sel_hi:[1,0]
	v_pk_mul_f32 v[30:31], v[30:31], v[66:67] op_sel_hi:[1,0]
	v_pk_mul_f32 v[28:29], v[28:29], v[66:67] op_sel_hi:[1,0]
	v_pk_mul_f32 v[26:27], v[26:27], v[66:67] op_sel_hi:[1,0]
	v_pk_mul_f32 v[24:25], v[24:25], v[66:67] op_sel_hi:[1,0]
	v_pk_mul_f32 v[22:23], v[22:23], v[66:67] op_sel_hi:[1,0]
	v_pk_mul_f32 v[20:21], v[20:21], v[66:67] op_sel_hi:[1,0]
	v_pk_mul_f32 v[18:19], v[18:19], v[66:67] op_sel_hi:[1,0]
	v_pk_mul_f32 v[48:49], v[48:49], v[66:67] op_sel_hi:[1,0]
	v_pk_mul_f32 v[46:47], v[46:47], v[66:67] op_sel_hi:[1,0]
	v_pk_mul_f32 v[44:45], v[44:45], v[66:67] op_sel_hi:[1,0]
	v_pk_mul_f32 v[42:43], v[42:43], v[66:67] op_sel_hi:[1,0]
	v_pk_mul_f32 v[40:41], v[40:41], v[66:67] op_sel_hi:[1,0]
	v_pk_mul_f32 v[38:39], v[38:39], v[66:67] op_sel_hi:[1,0]
	v_pk_mul_f32 v[36:37], v[36:37], v[66:67] op_sel_hi:[1,0]
	v_pk_mul_f32 v[34:35], v[34:35], v[66:67] op_sel_hi:[1,0]
	v_pk_mul_f32 v[64:65], v[64:65], v[66:67] op_sel_hi:[1,0]
	v_pk_mul_f32 v[62:63], v[62:63], v[66:67] op_sel_hi:[1,0]
	v_pk_mul_f32 v[60:61], v[60:61], v[66:67] op_sel_hi:[1,0]
	v_pk_mul_f32 v[58:59], v[58:59], v[66:67] op_sel_hi:[1,0]
	v_pk_mul_f32 v[56:57], v[56:57], v[66:67] op_sel_hi:[1,0]
	v_pk_mul_f32 v[54:55], v[54:55], v[66:67] op_sel_hi:[1,0]
	v_pk_mul_f32 v[52:53], v[52:53], v[66:67] op_sel_hi:[1,0]
	v_pk_mul_f32 v[50:51], v[50:51], v[66:67] op_sel_hi:[1,0]
	v_sub_f32_e32 v156, v156, v67
	v_sub_f32_e32 v157, v157, v67
	v_sub_f32_e32 v160, v160, v67
	v_sub_f32_e32 v161, v161, v67
	v_sub_f32_e32 v164, v164, v67
	v_sub_f32_e32 v165, v165, v67
	v_sub_f32_e32 v166, v166, v67
	v_sub_f32_e32 v167, v167, v67
	v_sub_f32_e32 v158, v158, v67
	v_sub_f32_e32 v159, v159, v67
	v_sub_f32_e32 v162, v162, v67
	v_sub_f32_e32 v163, v163, v67
	v_sub_f32_e32 v110, v110, v67
	v_sub_f32_e32 v111, v111, v67
	v_sub_f32_e32 v112, v112, v67
	v_sub_f32_e32 v113, v113, v67
	v_mul_f32_e32 v151, v151, v66
	v_mov_b32_e32 v66, v82
	v_mov_b32_e32 v67, v82
	v_mov_b32_e32 v68, v82
	v_mov_b32_e32 v69, v82
	v_mov_b32_e32 v70, v82
	v_mov_b32_e32 v71, v82
	v_mov_b32_e32 v72, v82
	v_mov_b32_e32 v73, v82
	v_mov_b32_e32 v74, v82
	v_mov_b32_e32 v75, v82
	v_mov_b32_e32 v76, v82
	v_mov_b32_e32 v77, v82
	v_mov_b32_e32 v78, v82
	v_mov_b32_e32 v79, v82
	v_mov_b32_e32 v80, v82
	v_mov_b32_e32 v81, v82
	s_branch .LBB0_593

; #define LAS __attribute__((address_space(3)))
; __device__ __forceinline__ float max3f(float a, float b, float c) { float r; asm("v_max3_f32 %0, %1, %2, %3" : "=v"(r) : "v"(a), "v"(b), "v"(c)); return r; }
; template <int DQK, int DV, bool BIAS> ...
;     ...
;         const LAS unsigned char* kb = lds + buf * KBUF + r32 * KP + hi * 16;
; #pragma unroll
;         for (int ks = 0; ks < NKS; ++ks) {
;             const bf16x8 k0 = *(const LAS bf16x8*)(kb + ks * 32), k1 = *(const LAS bf16x8*)(kb + 32 * KP + ks * 32);
;             if (ks == 0) { p0 = __builtin_amdgcn_mfma_f32_32x32x16_bf16(k0, qf[0], negm, 0, 0, 0); p1 = __builtin_amdgcn_mfma_f32_32x32x16_bf16(k1, qf[0], negm, 0, 0, 0); }
;             else { p0 = __builtin_amdgcn_mfma_f32_32x32x16_bf16(k0, qf[ks], p0, 0, 0, 0); p1 = __builtin_amdgcn_mfma_f32_32x32x16_bf16(k1, qf[ks], p1, 0, 0, 0); }
;         }
;         if (BIAS) {
;             asm volatile("s_nop 15\n\ts_nop 7" : "+v"(p0), "+v"(p1));
;             const float d0 = qp - (float)(t * 64 + 4 * hi);
; #pragma unroll
;             for (int r = 0; r < 16; ++r) { const float dk = d0 - (float)((r & 3) + 8 * (r >> 2)); p0[r] = p0[r] - sl2 * fabsf(dk); p1[r] = p1[r] - sl2 * fabsf(dk - 32.f); }
;         } else {
;             asm volatile("s_nop 15\n\ts_nop 7" : "+v"(p0), "+v"(p1));
;         }
;         float mxa = max3f(p0[0], p0[1], p1[0]), mxb = max3f(p0[2], p0[3], p1[1]); mxa = max3f(mxa, p1[2], p1[3]);
; #pragma unroll
;         for (int r = 4; r < 16; r += 4) { mxa = max3f(mxa, p0[r], p0[r + 1]); mxb = max3f(mxb, p0[r + 2], p0[r + 3]); mxa = max3f(mxa, p1[r], p1[r + 1]); mxb = max3f(mxb, p1[r + 2], p1[r + 3]); }
;         float mx = fmaxf(mxa, mxb);
;         if (__any(mx > 8.f)) {
.LBB0_596:
	ds_read_b128 v[196:199], v179 offset:9216
	ds_read_b128 v[200:203], v179 offset:9248
	v_add_f32_e32 v156, 0, v156
	v_add_f32_e32 v156, v157, v156
	v_add_f32_e32 v156, v160, v156
	s_waitcnt lgkmcnt(1)
	v_mfma_f32_32x32x16_bf16 v[98:113], v[196:199], v[114:117], v[66:81]
	ds_read_b128 v[196:199], v179 offset:13824
	ds_read_b128 v[204:207], v179 offset:13856
	v_add_f32_e32 v156, v161, v156
	v_add_f32_e32 v156, v164, v156
	v_add_f32_e32 v150, v150, v156
	v_add_f32_e32 v150, v165, v150
	v_add_f32_e32 v150, v166, v150
	v_add_f32_e32 v150, v167, v150
	s_waitcnt lgkmcnt(1)
	v_mfma_f32_32x32x16_bf16 v[82:97], v[196:199], v[114:117], v[66:81]
	v_add_f32_e32 v150, v181, v150
	v_add_f32_e32 v150, v182, v150
	v_add_f32_e32 v150, v158, v150
	v_add_f32_e32 v150, v159, v150
	ds_read_b128 v[164:167], v179 offset:9280
	v_add_f32_e32 v150, v162, v150
	v_add_f32_e32 v150, v163, v150
	v_mfma_f32_32x32x16_bf16 v[98:113], v[200:203], v[118:121], v[98:113]
	v_add_f32_e32 v150, v183, v150
	v_add_f32_e32 v150, v184, v150
	v_add_f32_e32 v150, v185, v150
	v_add_f32_e32 v150, v152, v150
	ds_read_b128 v[156:159], v179 offset:13888
	ds_read_b128 v[160:163], v179 offset:9312
	v_add_f32_e32 v150, v153, v150
	v_add_f32_e32 v150, v186, v150
	s_waitcnt lgkmcnt(3)
	v_mfma_f32_32x32x16_bf16 v[82:97], v[204:207], v[118:121], v[82:97]
	v_add_f32_e32 v150, v187, v150
	v_add_f32_e32 v150, v154, v150
	v_add_f32_e32 v150, v155, v150
	v_add_f32_e32 v150, v188, v150
	v_add_f32_e32 v150, v189, v150
	v_add_u32_e32 v152, 64, v177
	v_add_f32_e32 v150, v190, v150
	s_waitcnt lgkmcnt(2)
	v_mfma_f32_32x32x16_bf16 v[98:113], v[164:167], v[122:125], v[98:113]
	ds_read_b128 v[164:167], v179 offset:13920
	v_cvt_f32_u32_e32 v152, v152
	v_add_f32_e32 v150, v191, v150
	v_add_f32_e32 v150, v192, v150
	v_add_f32_e32 v150, v195, v150
	v_add_f32_e32 v150, v193, v150
	v_add_f32_e32 v150, v194, v150
	s_waitcnt lgkmcnt(2)
	v_mfma_f32_32x32x16_bf16 v[82:97], v[156:159], v[122:125], v[82:97]
	v_add_f32_e32 v158, v151, v150
	s_waitcnt lgkmcnt(1)
	v_mfma_f32_32x32x16_bf16 v[98:113], v[160:163], v[126:129], v[98:113]
	v_sub_f32_e32 v160, v176, v152
	v_add_f32_e32 v161, -1.0, v160
	v_and_b32_e32 v150, 0x7fffffff, v160
	v_and_b32_e32 v151, 0x7fffffff, v161
	s_waitcnt lgkmcnt(0)
	v_mfma_f32_32x32x16_bf16 v[82:97], v[164:167], v[126:129], v[82:97]
	s_nop 15
	s_nop 7
	s_nop 5
	v_pk_fma_f32 v[150:151], v[142:143], v[150:151], v[98:99] neg_lo:[1,0,0] neg_hi:[1,0,0]
	v_pk_add_f32 v[98:99], v[160:161], s[6:7] op_sel_hi:[1,0]
	s_nop 0
	v_fma_f32 v83, -v143, |v99|, v83
	v_fma_f32 v82, -v142, |v98|, v82
	s_nop 0
	v_pk_add_f32 v[98:99], v[160:161], s[8:9] op_sel_hi:[0,1]
	v_fma_f32 v153, -v143, |v99|, v101
	v_fma_f32 v152, -v142, |v98|, v100
	v_pk_add_f32 v[98:99], v[98:99], s[6:7] op_sel_hi:[1,0]
	v_fma_f32 v99, -v143, |v99|, v85
	v_fma_f32 v98, -v142, |v98|, v84
	v_pk_add_f32 v[84:85], v[160:161], s[10:11] op_sel_hi:[0,1]
	v_fma_f32 v155, -v143, |v85|, v103
	v_fma_f32 v154, -v142, |v84|, v102
	v_pk_add_f32 v[84:85], v[84:85], s[6:7] op_sel_hi:[1,0]
	v_fma_f32 v101, -v143, |v85|, v87
	v_fma_f32 v100, -v142, |v84|, v86
	v_pk_add_f32 v[84:85], v[160:161], s[22:23] op_sel_hi:[0,1]
	v_fma_f32 v157, -v143, |v85|, v105
	v_fma_f32 v156, -v142, |v84|, v104
	v_pk_add_f32 v[84:85], v[84:85], s[6:7] op_sel_hi:[1,0]
	v_fma_f32 v103, -v143, |v85|, v89
	v_fma_f32 v102, -v142, |v84|, v88
	v_pk_add_f32 v[84:85], v[160:161], s[34:35] op_sel_hi:[0,1]
	v_fma_f32 v105, -v143, |v85|, v107
	v_fma_f32 v104, -v142, |v84|, v106
	v_pk_add_f32 v[86:87], v[160:161], s[36:37] op_sel_hi:[0,1]
	v_pk_add_f32 v[84:85], v[84:85], s[6:7] op_sel_hi:[1,0]
	v_fma_f32 v107, -v143, |v87|, v109
	v_fma_f32 v106, -v142, |v86|, v108
	v_fma_f32 v85, -v143, |v85|, v91
	v_fma_f32 v84, -v142, |v84|, v90
	v_pk_add_f32 v[86:87], v[86:87], s[6:7] op_sel_hi:[1,0]
	v_pk_add_f32 v[88:89], v[160:161], s[38:39] op_sel_hi:[0,1]
	v_fma_f32 v87, -v143, |v87|, v93
	v_fma_f32 v86, -v142, |v86|, v92
	v_fma_f32 v93, -v143, |v89|, v111
	v_fma_f32 v92, -v142, |v88|, v110
	v_pk_add_f32 v[88:89], v[88:89], s[6:7] op_sel_hi:[1,0]
	v_fma_f32 v89, -v143, |v89|, v95
	v_fma_f32 v88, -v142, |v88|, v94
	v_pk_add_f32 v[90:91], v[160:161], s[40:41] op_sel_hi:[0,1]
	v_fma_f32 v95, -v143, |v91|, v113
	v_fma_f32 v94, -v142, |v90|, v112
	v_pk_add_f32 v[90:91], v[90:91], s[6:7] op_sel_hi:[1,0]
	v_fma_f32 v91, -v143, |v91|, v97
	v_fma_f32 v90, -v142, |v90|, v96
	v_max3_f32 v96, v150, v151, v82
	v_max3_f32 v97, v152, v153, v83
	v_max3_f32 v96, v96, v98, v99
	v_max3_f32 v97, v97, v156, v157
	v_max3_f32 v96, v96, v154, v155
	v_max3_f32 v97, v97, v102, v103
	v_max3_f32 v96, v96, v100, v101
	v_max3_f32 v97, v97, v106, v107
	v_max3_f32 v96, v96, v104, v105
	v_max3_f32 v97, v97, v86, v87
	v_max3_f32 v96, v96, v84, v85
	v_max3_f32 v97, v97, v94, v95
	v_max3_f32 v96, v96, v92, v93
	v_max3_f32 v97, v97, v90, v91
	v_max3_f32 v96, v96, v88, v89
	v_max_f32_e32 v96, v96, v97
	v_cmp_gt_f32_e32 vcc, 0xc3400000, v96
	s_cmp_eq_u64 vcc, exec
	s_cbranch_scc1 .Lsk2_p4a2
; template <int DQK, int DV, bool BIAS> ...
;     ...
;         if (__any(mx > 8.f)) {
;             mx = fmaxf(mx, __shfl_xor(mx, 32));
;             const float dl = fmaxf(mx, 0.f); mhat += dl;
;             const float f = __builtin_amdgcn_exp2f(-dl);
; #pragma unroll
;             for (int r = 0; r < 16; ++r) { p0[r] -= dl; p1[r] -= dl; negm[r] = -mhat; }
;             l *= f;
; #pragma unroll
;             for (int d = 0; d < NDT; ++d)
; #pragma unroll
;                 for (int r = 0; r < 16; ++r) o[d][r] *= f;
;         }
	v_cmp_lt_f32_e32 vcc, s44, v96
	s_cbranch_vccz .LBB0_587
	ds_bpermute_b32 v66, v168, v96
	s_waitcnt lgkmcnt(0)
	v_max3_f32 v67, v96, v66, 0
	v_exp_f32_e64 v68, -v67
	v_add_f32_e32 v180, v180, v67
	v_xor_b32_e32 v66, 0x80000000, v180
	v_sub_f32_e32 v82, v82, v67
	v_sub_f32_e32 v83, v83, v67
	v_sub_f32_e32 v98, v98, v67
	v_sub_f32_e32 v99, v99, v67
	v_sub_f32_e32 v100, v100, v67
	v_sub_f32_e32 v101, v101, v67
	v_sub_f32_e32 v102, v102, v67
	v_sub_f32_e32 v103, v103, v67
	v_sub_f32_e32 v84, v84, v67
	v_sub_f32_e32 v85, v85, v67
	v_sub_f32_e32 v86, v86, v67
	v_sub_f32_e32 v87, v87, v67
	v_sub_f32_e32 v88, v88, v67
	v_sub_f32_e32 v89, v89, v67
	v_sub_f32_e32 v90, v90, v67
	v_sub_f32_e32 v91, v91, v67
	v_pk_mul_f32 v[16:17], v[16:17], v[68:69] op_sel_hi:[1,0]
	v_pk_mul_f32 v[14:15], v[14:15], v[68:69] op_sel_hi:[1,0]
	v_pk_mul_f32 v[12:13], v[12:13], v[68:69] op_sel_hi:[1,0]
	v_pk_mul_f32 v[10:11], v[10:11], v[68:69] op_sel_hi:[1,0]
	v_pk_mul_f32 v[8:9], v[8:9], v[68:69] op_sel_hi:[1,0]
	v_pk_mul_f32 v[6:7], v[6:7], v[68:69] op_sel_hi:[1,0]
	v_pk_mul_f32 v[4:5], v[4:5], v[68:69] op_sel_hi:[1,0]
	v_pk_mul_f32 v[2:3], v[2:3], v[68:69] op_sel_hi:[1,0]
	v_pk_mul_f32 v[32:33], v[32:33], v[68:69] op_sel_hi:[1,0]
	v_pk_mul_f32 v[30:31], v[30:31], v[68:69] op_sel_hi:[1,0]
	v_pk_mul_f32 v[28:29], v[28:29], v[68:69] op_sel_hi:[1,0]
	v_pk_mul_f32 v[26:27], v[26:27], v[68:69] op_sel_hi:[1,0]
	v_pk_mul_f32 v[24:25], v[24:25], v[68:69] op_sel_hi:[1,0]
	v_pk_mul_f32 v[22:23], v[22:23], v[68:69] op_sel_hi:[1,0]
	v_pk_mul_f32 v[20:21], v[20:21], v[68:69] op_sel_hi:[1,0]
	v_pk_mul_f32 v[18:19], v[18:19], v[68:69] op_sel_hi:[1,0]
	v_pk_mul_f32 v[48:49], v[48:49], v[68:69] op_sel_hi:[1,0]
	v_pk_mul_f32 v[46:47], v[46:47], v[68:69] op_sel_hi:[1,0]
	v_pk_mul_f32 v[44:45], v[44:45], v[68:69] op_sel_hi:[1,0]
	v_pk_mul_f32 v[42:43], v[42:43], v[68:69] op_sel_hi:[1,0]
	v_pk_mul_f32 v[40:41], v[40:41], v[68:69] op_sel_hi:[1,0]
	v_pk_mul_f32 v[38:39], v[38:39], v[68:69] op_sel_hi:[1,0]
	v_pk_mul_f32 v[36:37], v[36:37], v[68:69] op_sel_hi:[1,0]
	v_pk_mul_f32 v[34:35], v[34:35], v[68:69] op_sel_hi:[1,0]
	v_pk_mul_f32 v[64:65], v[64:65], v[68:69] op_sel_hi:[1,0]
	v_pk_mul_f32 v[62:63], v[62:63], v[68:69] op_sel_hi:[1,0]
	v_pk_mul_f32 v[60:61], v[60:61], v[68:69] op_sel_hi:[1,0]
	v_pk_mul_f32 v[58:59], v[58:59], v[68:69] op_sel_hi:[1,0]
	v_pk_mul_f32 v[56:57], v[56:57], v[68:69] op_sel_hi:[1,0]
	v_pk_mul_f32 v[54:55], v[54:55], v[68:69] op_sel_hi:[1,0]
	v_pk_mul_f32 v[52:53], v[52:53], v[68:69] op_sel_hi:[1,0]
	v_pk_mul_f32 v[50:51], v[50:51], v[68:69] op_sel_hi:[1,0]
	v_sub_f32_e32 v150, v150, v67
	v_sub_f32_e32 v151, v151, v67
	v_sub_f32_e32 v152, v152, v67
	v_sub_f32_e32 v153, v153, v67
	v_sub_f32_e32 v154, v154, v67
	v_sub_f32_e32 v155, v155, v67
	v_sub_f32_e32 v156, v156, v67
	v_sub_f32_e32 v157, v157, v67
	v_sub_f32_e32 v104, v104, v67
	v_sub_f32_e32 v105, v105, v67
	v_sub_f32_e32 v106, v106, v67
	v_sub_f32_e32 v107, v107, v67
	v_sub_f32_e32 v92, v92, v67
	v_sub_f32_e32 v93, v93, v67
	v_sub_f32_e32 v94, v94, v67
	v_sub_f32_e32 v95, v95, v67
	v_mul_f32_e32 v158, v158, v68
	v_mov_b32_e32 v67, v66
	v_mov_b32_e32 v68, v66
	v_mov_b32_e32 v69, v66
	v_mov_b32_e32 v70, v66
	v_mov_b32_e32 v71, v66
	v_mov_b32_e32 v72, v66
	v_mov_b32_e32 v73, v66
	v_mov_b32_e32 v74, v66
	v_mov_b32_e32 v75, v66
	v_mov_b32_e32 v76, v66
	v_mov_b32_e32 v77, v66
	v_mov_b32_e32 v78, v66
	v_mov_b32_e32 v79, v66
	v_mov_b32_e32 v80, v66
	v_mov_b32_e32 v81, v66
	s_branch .LBB0_587

; #define LAS __attribute__((address_space(3)))
; __device__ __forceinline__ float max3f(float a, float b, float c) { float r; asm("v_max3_f32 %0, %1, %2, %3" : "=v"(r) : "v"(a), "v"(b), "v"(c)); return r; }
; template <int DQK, int DV, bool BIAS> ...
;     ...
;         const LAS unsigned char* kb = lds + buf * KBUF + r32 * KP + hi * 16;
; #pragma unroll
;         for (int ks = 0; ks < NKS; ++ks) {
;             const bf16x8 k0 = *(const LAS bf16x8*)(kb + ks * 32), k1 = *(const LAS bf16x8*)(kb + 32 * KP + ks * 32);
;             if (ks == 0) { p0 = __builtin_amdgcn_mfma_f32_32x32x16_bf16(k0, qf[0], negm, 0, 0, 0); p1 = __builtin_amdgcn_mfma_f32_32x32x16_bf16(k1, qf[0], negm, 0, 0, 0); }
;             else { p0 = __builtin_amdgcn_mfma_f32_32x32x16_bf16(k0, qf[ks], p0, 0, 0, 0); p1 = __builtin_amdgcn_mfma_f32_32x32x16_bf16(k1, qf[ks], p1, 0, 0, 0); }
;         }
;         if (BIAS) {
;             asm volatile("s_nop 15\n\ts_nop 7" : "+v"(p0), "+v"(p1));
;             const float d0 = qp - (float)(t * 64 + 4 * hi);
; #pragma unroll
;             for (int r = 0; r < 16; ++r) { const float dk = d0 - (float)((r & 3) + 8 * (r >> 2)); p0[r] = p0[r] - sl2 * fabsf(dk); p1[r] = p1[r] - sl2 * fabsf(dk - 32.f); }
;         } else {
;             asm volatile("s_nop 15\n\ts_nop 7" : "+v"(p0), "+v"(p1));
;         }
;         float mxa = max3f(p0[0], p0[1], p1[0]), mxb = max3f(p0[2], p0[3], p1[1]); mxa = max3f(mxa, p1[2], p1[3]);
; #pragma unroll
;         for (int r = 4; r < 16; r += 4) { mxa = max3f(mxa, p0[r], p0[r + 1]); mxb = max3f(mxb, p0[r + 2], p0[r + 3]); mxa = max3f(mxa, p1[r], p1[r + 1]); mxb = max3f(mxb, p1[r + 2], p1[r + 3]); }
;         float mx = fmaxf(mxa, mxb);
;         if (__any(mx > 8.f)) {
;             mx = fmaxf(mx, __shfl_xor(mx, 32));
;             const float dl = fmaxf(mx, 0.f); mhat += dl;
;             const float f = __builtin_amdgcn_exp2f(-dl);
; #pragma unroll
;             for (int r = 0; r < 16; ++r) { p0[r] -= dl; p1[r] -= dl; negm[r] = -mhat; }
;             l *= f;
; #pragma unroll
;             for (int d = 0; d < NDT; ++d)
; #pragma unroll
;                 for (int r = 0; r < 16; ++r) o[d][r] *= f;
;         }
.LBB0_604:
	ds_read_b128 v[34:37], v130
	ds_read_b128 v[38:41], v130 offset:32
	s_waitcnt lgkmcnt(1)
	v_mfma_f32_32x32x16_bf16 v[82:97], v[34:37], v[98:101], v[50:65]
	ds_read_b128 v[34:37], v130 offset:4608
	ds_read_b128 v[42:45], v130 offset:4640
	s_waitcnt lgkmcnt(1)
	v_mfma_f32_32x32x16_bf16 v[66:81], v[34:37], v[98:101], v[50:65]
	v_mfma_f32_32x32x16_bf16 v[82:97], v[38:41], v[102:105], v[82:97]
	ds_read_b128 v[34:37], v130 offset:64
	ds_read_b128 v[38:41], v130 offset:96
	s_waitcnt lgkmcnt(2)
	v_mfma_f32_32x32x16_bf16 v[66:81], v[42:45], v[102:105], v[66:81]
	s_waitcnt lgkmcnt(1)
	v_mfma_f32_32x32x16_bf16 v[82:97], v[34:37], v[106:109], v[82:97]
	ds_read_b128 v[34:37], v130 offset:4672
	ds_read_b128 v[42:45], v130 offset:4704
	s_waitcnt lgkmcnt(1)
	v_mfma_f32_32x32x16_bf16 v[66:81], v[34:37], v[106:109], v[66:81]
	v_mfma_f32_32x32x16_bf16 v[82:97], v[38:41], v[110:113], v[82:97]
	s_waitcnt lgkmcnt(0)
	v_mfma_f32_32x32x16_bf16 v[66:81], v[42:45], v[110:113], v[66:81]
	s_nop 15
	s_nop 7
	s_nop 0
	v_max3_f32 v34, v82, v83, v66
	v_max3_f32 v35, v84, v85, v67
	v_max3_f32 v34, v34, v68, v69
	v_max3_f32 v35, v35, v88, v89
	v_max3_f32 v34, v34, v86, v87
	v_max3_f32 v35, v35, v72, v73
	v_max3_f32 v34, v34, v70, v71
	v_max3_f32 v35, v35, v92, v93
	v_max3_f32 v34, v34, v90, v91
	v_max3_f32 v35, v35, v76, v77
	v_max3_f32 v34, v34, v74, v75
	v_max3_f32 v35, v35, v96, v97
	v_max3_f32 v34, v34, v94, v95
	v_max3_f32 v35, v35, v80, v81
	v_max3_f32 v34, v34, v78, v79
	v_max_f32_e32 v34, v34, v35
	v_cmp_lt_f32_e32 vcc, s47, v34
	s_cbranch_vccz .LBB0_606
	ds_bpermute_b32 v35, v168, v34
	s_waitcnt lgkmcnt(0)
	v_max3_f32 v36, v34, v35, 0
	v_exp_f32_e64 v38, -v36
	v_add_f32_e32 v143, v143, v36
	v_xor_b32_e32 v34, 0x80000000, v143
	v_pk_add_f32 v[82:83], v[82:83], v[36:37] op_sel_hi:[1,0] neg_lo:[0,1] neg_hi:[0,1]
	v_pk_add_f32 v[66:67], v[66:67], v[36:37] op_sel_hi:[1,0] neg_lo:[0,1] neg_hi:[0,1]
	v_pk_add_f32 v[84:85], v[84:85], v[36:37] op_sel_hi:[1,0] neg_lo:[0,1] neg_hi:[0,1]
	v_pk_add_f32 v[68:69], v[68:69], v[36:37] op_sel_hi:[1,0] neg_lo:[0,1] neg_hi:[0,1]
	v_pk_add_f32 v[86:87], v[86:87], v[36:37] op_sel_hi:[1,0] neg_lo:[0,1] neg_hi:[0,1]
	v_pk_add_f32 v[70:71], v[70:71], v[36:37] op_sel_hi:[1,0] neg_lo:[0,1] neg_hi:[0,1]
	v_pk_add_f32 v[88:89], v[88:89], v[36:37] op_sel_hi:[1,0] neg_lo:[0,1] neg_hi:[0,1]
	v_pk_add_f32 v[72:73], v[72:73], v[36:37] op_sel_hi:[1,0] neg_lo:[0,1] neg_hi:[0,1]
	v_pk_add_f32 v[90:91], v[90:91], v[36:37] op_sel_hi:[1,0] neg_lo:[0,1] neg_hi:[0,1]
	v_pk_add_f32 v[74:75], v[74:75], v[36:37] op_sel_hi:[1,0] neg_lo:[0,1] neg_hi:[0,1]
	v_pk_add_f32 v[92:93], v[92:93], v[36:37] op_sel_hi:[1,0] neg_lo:[0,1] neg_hi:[0,1]
	v_pk_add_f32 v[76:77], v[76:77], v[36:37] op_sel_hi:[1,0] neg_lo:[0,1] neg_hi:[0,1]
	v_pk_add_f32 v[94:95], v[94:95], v[36:37] op_sel_hi:[1,0] neg_lo:[0,1] neg_hi:[0,1]
	v_pk_add_f32 v[78:79], v[78:79], v[36:37] op_sel_hi:[1,0] neg_lo:[0,1] neg_hi:[0,1]
	v_pk_add_f32 v[96:97], v[96:97], v[36:37] op_sel_hi:[1,0] neg_lo:[0,1] neg_hi:[0,1]
	v_pk_add_f32 v[80:81], v[80:81], v[36:37] op_sel_hi:[1,0] neg_lo:[0,1] neg_hi:[0,1]
	v_pk_mul_f32 v[16:17], v[16:17], v[38:39] op_sel_hi:[1,0]
	v_pk_mul_f32 v[14:15], v[14:15], v[38:39] op_sel_hi:[1,0]
	v_pk_mul_f32 v[12:13], v[12:13], v[38:39] op_sel_hi:[1,0]
	v_pk_mul_f32 v[10:11], v[10:11], v[38:39] op_sel_hi:[1,0]
	v_pk_mul_f32 v[8:9], v[8:9], v[38:39] op_sel_hi:[1,0]
	v_pk_mul_f32 v[6:7], v[6:7], v[38:39] op_sel_hi:[1,0]
	v_pk_mul_f32 v[4:5], v[4:5], v[38:39] op_sel_hi:[1,0]
	v_pk_mul_f32 v[2:3], v[2:3], v[38:39] op_sel_hi:[1,0]
	v_pk_mul_f32 v[32:33], v[32:33], v[38:39] op_sel_hi:[1,0]
	v_pk_mul_f32 v[30:31], v[30:31], v[38:39] op_sel_hi:[1,0]
	v_pk_mul_f32 v[28:29], v[28:29], v[38:39] op_sel_hi:[1,0]
	v_pk_mul_f32 v[26:27], v[26:27], v[38:39] op_sel_hi:[1,0]
	v_pk_mul_f32 v[24:25], v[24:25], v[38:39] op_sel_hi:[1,0]
	v_pk_mul_f32 v[22:23], v[22:23], v[38:39] op_sel_hi:[1,0]
	v_pk_mul_f32 v[20:21], v[20:21], v[38:39] op_sel_hi:[1,0]
	v_pk_mul_f32 v[18:19], v[18:19], v[38:39] op_sel_hi:[1,0]
	v_mul_f32_e32 v144, v144, v38
	v_mov_b32_e32 v35, v34
	v_mov_b32_e32 v36, v34
	v_mov_b32_e32 v37, v34
	v_mov_b32_e32 v38, v34
	v_mov_b32_e32 v39, v34
	v_mov_b32_e32 v40, v34
	v_mov_b32_e32 v41, v34
	v_mov_b32_e32 v42, v34
	v_mov_b32_e32 v43, v34
	v_mov_b32_e32 v44, v34
	v_mov_b32_e32 v45, v34
	v_mov_b32_e32 v46, v34
	v_mov_b32_e32 v47, v34
	v_mov_b32_e32 v48, v34
	v_mov_b32_e32 v49, v34
	v_mov_b32_e32 v50, v34
	v_mov_b32_e32 v51, v34
	v_mov_b32_e32 v52, v34
	v_mov_b32_e32 v53, v34
	v_mov_b32_e32 v54, v34
	v_mov_b32_e32 v55, v34
	v_mov_b32_e32 v56, v34
	v_mov_b32_e32 v57, v34
	v_mov_b32_e32 v58, v34
	v_mov_b32_e32 v59, v34
	v_mov_b32_e32 v60, v34
	v_mov_b32_e32 v61, v34
	v_mov_b32_e32 v62, v34
	v_mov_b32_e32 v63, v34
	v_mov_b32_e32 v64, v34
	v_mov_b32_e32 v65, v34
	s_branch .LBB0_607

; #define LAS __attribute__((address_space(3)))
; template <int DQK, int DV, bool BIAS> ...
;     ...
;         const LAS unsigned char* kb = lds + buf * KBUF + r32 * KP + hi * 16;
; #pragma unroll
;         for (int ks = 0; ks < NKS; ++ks) {
;             const bf16x8 k0 = *(const LAS bf16x8*)(kb + ks * 32), k1 = *(const LAS bf16x8*)(kb + 32 * KP + ks * 32);
;             if (ks == 0) { p0 = __builtin_amdgcn_mfma_f32_32x32x16_bf16(k0, qf[0], negm, 0, 0, 0); p1 = __builtin_amdgcn_mfma_f32_32x32x16_bf16(k1, qf[0], negm, 0, 0, 0); }
;             else { p0 = __builtin_amdgcn_mfma_f32_32x32x16_bf16(k0, qf[ks], p0, 0, 0, 0); p1 = __builtin_amdgcn_mfma_f32_32x32x16_bf16(k1, qf[ks], p1, 0, 0, 0); }
;         }
;         if (BIAS) {
;             asm volatile("s_nop 15\n\ts_nop 7" : "+v"(p0), "+v"(p1));
;             const float d0 = qp - (float)(t * 64 + 4 * hi);
; #pragma unroll
;             for (int r = 0; r < 16; ++r) { const float dk = d0 - (float)((r & 3) + 8 * (r >> 2)); p0[r] = p0[r] - sl2 * fabsf(dk); p1[r] = p1[r] - sl2 * fabsf(dk - 32.f); }
;         } else {
;             asm volatile("s_nop 15\n\ts_nop 7" : "+v"(p0), "+v"(p1));
;         }
;     ...
;             const LAS unsigned char* vbase = lds + VOFF + vcur * VBUF + (4 * hi + ((lane & 15) >> 2)) * 64 + ((lane >> 4) & 1) * 32 + (lane & 3) * 8;
;             float ls = 0.f;
; #pragma unroll
;             for (int hs = 0; hs < 4; ++hs) {
;                 float e[8];
; #pragma unroll
;                 for (int j = 0; j < 8; ++j) { e[j] = __builtin_amdgcn_exp2f(hs < 2 ? p0[8 * (hs & 1) + j] : p1[8 * (hs & 1) + j]); ls += e[j]; }
;                 pw[hs].x = cvtpk(e[0], e[1]); pw[hs].y = cvtpk(e[2], e[3]); pw[hs].z = cvtpk(e[4], e[5]); pw[hs].w = cvtpk(e[6], e[7]);
;                 const bf16x8 pbv = __builtin_bit_cast(bf16x8, pw[hs]);
; #pragma unroll
;                 for (int d = 0; d < NDT; ++d) { const LAS unsigned char* vp = vbase + d * 4096 + hs * 1024;
;                     const v4i16_t a0 = __builtin_amdgcn_ds_read_tr16_b64_v4i16((LAS v4i16_t*)vp), a1 = __builtin_amdgcn_ds_read_tr16_b64_v4i16((LAS v4i16_t*)(vp + 512));
;                     const bf16x8 av = {a0[0], a0[1], a0[2], a0[3], a1[0], a1[1], a1[2], a1[3]};
;                     o[d] = __builtin_amdgcn_mfma_f32_32x32x16_bf16(av, pbv, o[d], 0, 0, 0); }
;                 __builtin_amdgcn_sched_barrier(0);
;             }
;             l += ls;
.LBB0_607:
	v_exp_f32_e32 v145, v82
	v_exp_f32_e32 v147, v83
	v_exp_f32_e32 v152, v84
	v_exp_f32_e32 v153, v85
	v_exp_f32_e32 v154, v86
	v_exp_f32_e32 v155, v87
	ds_read_b64_tr_b16 v[82:83], v141 offset:36864
	ds_read_b64_tr_b16 v[84:85], v141 offset:37376
	v_exp_f32_e32 v156, v88
	v_exp_f32_e32 v157, v89
	ds_read_b64_tr_b16 v[148:149], v141 offset:40960
	ds_read_b64_tr_b16 v[150:151], v141 offset:41472
	v_cvt_pk_bf16_f32 v86, v145, v147
	v_cvt_pk_bf16_f32 v87, v152, v153
	v_cvt_pk_bf16_f32 v88, v154, v155
	v_cvt_pk_bf16_f32 v89, v156, v157
	s_waitcnt lgkmcnt(2)
	s_nop 0
	v_mfma_f32_32x32x16_bf16 v[18:33], v[82:85], v[86:89], v[18:33]
	v_add_f32_e32 v82, 0, v145
	v_add_f32_e32 v82, v147, v82
	v_add_f32_e32 v82, v152, v82
	v_add_f32_e32 v82, v153, v82
	v_add_f32_e32 v82, v154, v82
	v_add_f32_e32 v82, v155, v82
	v_add_f32_e32 v82, v156, v82
	s_waitcnt lgkmcnt(0)
	v_mfma_f32_32x32x16_bf16 v[2:17], v[148:151], v[86:89], v[2:17]
	v_add_f32_e32 v145, v157, v82
	v_exp_f32_e32 v147, v90
	v_exp_f32_e32 v148, v91
	v_exp_f32_e32 v149, v92
	v_exp_f32_e32 v150, v93
	v_exp_f32_e32 v94, v94
	v_exp_f32_e32 v95, v95
	ds_read_b64_tr_b16 v[82:83], v141 offset:37888
	ds_read_b64_tr_b16 v[84:85], v141 offset:38400
	v_exp_f32_e32 v96, v96
	v_exp_f32_e32 v97, v97
	ds_read_b64_tr_b16 v[90:91], v141 offset:41984
	ds_read_b64_tr_b16 v[92:93], v141 offset:42496
	v_cvt_pk_bf16_f32 v86, v147, v148
	v_cvt_pk_bf16_f32 v87, v149, v150
	v_cvt_pk_bf16_f32 v88, v94, v95
	v_cvt_pk_bf16_f32 v89, v96, v97
	s_waitcnt lgkmcnt(2)
	s_nop 0
	v_mfma_f32_32x32x16_bf16 v[18:33], v[82:85], v[86:89], v[18:33]
	v_add_f32_e32 v82, v147, v145
	v_add_f32_e32 v82, v148, v82
	v_add_f32_e32 v82, v149, v82
	v_add_f32_e32 v82, v150, v82
	v_add_f32_e32 v82, v94, v82
	v_add_f32_e32 v82, v95, v82
	v_add_f32_e32 v82, v96, v82
	s_waitcnt lgkmcnt(0)
	v_mfma_f32_32x32x16_bf16 v[2:17], v[90:93], v[86:89], v[2:17]
	v_add_f32_e32 v86, v97, v82
	v_exp_f32_e32 v87, v66
	v_exp_f32_e32 v88, v67
	v_exp_f32_e32 v89, v68
	v_exp_f32_e32 v90, v69
	v_exp_f32_e32 v91, v70
	v_exp_f32_e32 v92, v71
	ds_read_b64_tr_b16 v[66:67], v141 offset:38912
	ds_read_b64_tr_b16 v[68:69], v141 offset:39424
	v_exp_f32_e32 v93, v72
	v_exp_f32_e32 v94, v73
	ds_read_b64_tr_b16 v[82:83], v141 offset:43008
	ds_read_b64_tr_b16 v[84:85], v141 offset:43520
	v_cvt_pk_bf16_f32 v70, v87, v88
	v_cvt_pk_bf16_f32 v71, v89, v90
	v_cvt_pk_bf16_f32 v72, v91, v92
	v_cvt_pk_bf16_f32 v73, v93, v94
	s_waitcnt lgkmcnt(2)
	s_nop 0
	v_mfma_f32_32x32x16_bf16 v[18:33], v[66:69], v[70:73], v[18:33]
	v_add_f32_e32 v66, v87, v86
	v_add_f32_e32 v66, v88, v66
	v_add_f32_e32 v66, v89, v66
	v_add_f32_e32 v66, v90, v66
	v_add_f32_e32 v66, v91, v66
	v_add_f32_e32 v66, v92, v66
	v_add_f32_e32 v66, v93, v66
	s_waitcnt lgkmcnt(0)
	v_mfma_f32_32x32x16_bf16 v[2:17], v[82:85], v[70:73], v[2:17]
	v_add_f32_e32 v82, v94, v66
	v_exp_f32_e32 v83, v74
	v_exp_f32_e32 v84, v75
	v_exp_f32_e32 v85, v76
	v_exp_f32_e32 v86, v77
	v_exp_f32_e32 v78, v78
	v_exp_f32_e32 v79, v79
	ds_read_b64_tr_b16 v[66:67], v141 offset:39936
	ds_read_b64_tr_b16 v[68:69], v141 offset:40448
	v_exp_f32_e32 v80, v80
	v_exp_f32_e32 v81, v81
	ds_read_b64_tr_b16 v[74:75], v141 offset:44032
	ds_read_b64_tr_b16 v[76:77], v141 offset:44544
	v_cvt_pk_bf16_f32 v70, v83, v84
	v_cvt_pk_bf16_f32 v71, v85, v86
	v_cvt_pk_bf16_f32 v72, v78, v79
	v_cvt_pk_bf16_f32 v73, v80, v81
	s_waitcnt lgkmcnt(2)
	s_nop 0
	v_mfma_f32_32x32x16_bf16 v[18:33], v[66:69], v[70:73], v[18:33]
	v_add_f32_e32 v66, v83, v82
	v_add_f32_e32 v66, v84, v66
	v_add_f32_e32 v66, v85, v66
	v_add_f32_e32 v66, v86, v66
	v_add_f32_e32 v66, v78, v66
	v_add_f32_e32 v66, v79, v66
	v_add_f32_e32 v66, v80, v66
	s_waitcnt lgkmcnt(0)
	v_mfma_f32_32x32x16_bf16 v[2:17], v[74:77], v[70:73], v[2:17]
	v_add_f32_e32 v145, v81, v66
	ds_read_b128 v[66:69], v130 offset:9216
	ds_read_b128 v[148:151], v130 offset:9248
	ds_read_b128 v[152:155], v130 offset:13824
	ds_read_b128 v[156:159], v130 offset:13856
	v_add_f32_e32 v144, v144, v145
	s_waitcnt lgkmcnt(3)
	v_mfma_f32_32x32x16_bf16 v[82:97], v[66:69], v[98:101], v[34:49]
	s_waitcnt lgkmcnt(1)
	v_mfma_f32_32x32x16_bf16 v[66:81], v[152:155], v[98:101], v[34:49]
	v_mfma_f32_32x32x16_bf16 v[82:97], v[148:151], v[102:105], v[82:97]
	ds_read_b128 v[148:151], v130 offset:9280
	ds_read_b128 v[152:155], v130 offset:9312
	s_waitcnt lgkmcnt(2)
	v_mfma_f32_32x32x16_bf16 v[66:81], v[156:159], v[102:105], v[66:81]
	s_waitcnt lgkmcnt(1)
	v_mfma_f32_32x32x16_bf16 v[82:97], v[148:151], v[106:109], v[82:97]
	ds_read_b128 v[148:151], v130 offset:13888
	ds_read_b128 v[156:159], v130 offset:13920
	s_waitcnt lgkmcnt(1)
	v_mfma_f32_32x32x16_bf16 v[66:81], v[148:151], v[106:109], v[66:81]
	v_mfma_f32_32x32x16_bf16 v[82:97], v[152:155], v[110:113], v[82:97]
	s_waitcnt lgkmcnt(0)
	v_mfma_f32_32x32x16_bf16 v[66:81], v[156:159], v[110:113], v[66:81]
	s_nop 15
	s_nop 7
	s_nop 0
	v_max3_f32 v145, v82, v83, v66
	v_max3_f32 v147, v84, v85, v67
	v_max3_f32 v145, v145, v68, v69
	v_max3_f32 v147, v147, v88, v89
	v_max3_f32 v145, v145, v86, v87
	v_max3_f32 v147, v147, v72, v73
	v_max3_f32 v145, v145, v70, v71
	v_max3_f32 v147, v147, v92, v93
	v_max3_f32 v145, v145, v90, v91
	v_max3_f32 v147, v147, v76, v77
	v_max3_f32 v145, v145, v74, v75
	v_max3_f32 v147, v147, v96, v97
	v_max3_f32 v145, v145, v94, v95
	v_max3_f32 v147, v147, v80, v81
	v_max3_f32 v145, v145, v78, v79
	v_max_f32_e32 v145, v145, v147
	v_cmp_lt_f32_e32 vcc, s47, v145
	s_cbranch_vccz .LBB0_609
; template <int DQK, int DV, bool BIAS> ...
;     ...
;         if (__any(mx > 8.f)) {
;             mx = fmaxf(mx, __shfl_xor(mx, 32));
;             const float dl = fmaxf(mx, 0.f); mhat += dl;
;             const float f = __builtin_amdgcn_exp2f(-dl);
; #pragma unroll
;             for (int r = 0; r < 16; ++r) { p0[r] -= dl; p1[r] -= dl; negm[r] = -mhat; }
;             l *= f;
; #pragma unroll
;             for (int d = 0; d < NDT; ++d)
; #pragma unroll
;                 for (int r = 0; r < 16; ++r) o[d][r] *= f;
;         }
	ds_bpermute_b32 v34, v168, v145
	s_waitcnt lgkmcnt(0)
	v_max3_f32 v36, v145, v34, 0
	v_exp_f32_e64 v38, -v36
	v_add_f32_e32 v143, v143, v36
	v_xor_b32_e32 v34, 0x80000000, v143
	v_pk_add_f32 v[82:83], v[82:83], v[36:37] op_sel_hi:[1,0] neg_lo:[0,1] neg_hi:[0,1]
	v_pk_add_f32 v[66:67], v[66:67], v[36:37] op_sel_hi:[1,0] neg_lo:[0,1] neg_hi:[0,1]
	v_pk_add_f32 v[84:85], v[84:85], v[36:37] op_sel_hi:[1,0] neg_lo:[0,1] neg_hi:[0,1]
	v_pk_add_f32 v[68:69], v[68:69], v[36:37] op_sel_hi:[1,0] neg_lo:[0,1] neg_hi:[0,1]
	v_pk_add_f32 v[86:87], v[86:87], v[36:37] op_sel_hi:[1,0] neg_lo:[0,1] neg_hi:[0,1]
	v_pk_add_f32 v[70:71], v[70:71], v[36:37] op_sel_hi:[1,0] neg_lo:[0,1] neg_hi:[0,1]
	v_pk_add_f32 v[88:89], v[88:89], v[36:37] op_sel_hi:[1,0] neg_lo:[0,1] neg_hi:[0,1]
	v_pk_add_f32 v[72:73], v[72:73], v[36:37] op_sel_hi:[1,0] neg_lo:[0,1] neg_hi:[0,1]
	v_pk_add_f32 v[90:91], v[90:91], v[36:37] op_sel_hi:[1,0] neg_lo:[0,1] neg_hi:[0,1]
	v_pk_add_f32 v[74:75], v[74:75], v[36:37] op_sel_hi:[1,0] neg_lo:[0,1] neg_hi:[0,1]
	v_pk_add_f32 v[92:93], v[92:93], v[36:37] op_sel_hi:[1,0] neg_lo:[0,1] neg_hi:[0,1]
	v_pk_add_f32 v[76:77], v[76:77], v[36:37] op_sel_hi:[1,0] neg_lo:[0,1] neg_hi:[0,1]
	v_pk_add_f32 v[94:95], v[94:95], v[36:37] op_sel_hi:[1,0] neg_lo:[0,1] neg_hi:[0,1]
	v_pk_add_f32 v[78:79], v[78:79], v[36:37] op_sel_hi:[1,0] neg_lo:[0,1] neg_hi:[0,1]
	v_pk_add_f32 v[96:97], v[96:97], v[36:37] op_sel_hi:[1,0] neg_lo:[0,1] neg_hi:[0,1]
	v_pk_add_f32 v[80:81], v[80:81], v[36:37] op_sel_hi:[1,0] neg_lo:[0,1] neg_hi:[0,1]
	v_pk_mul_f32 v[16:17], v[16:17], v[38:39] op_sel_hi:[1,0]
	v_pk_mul_f32 v[14:15], v[14:15], v[38:39] op_sel_hi:[1,0]
	v_pk_mul_f32 v[12:13], v[12:13], v[38:39] op_sel_hi:[1,0]
	v_pk_mul_f32 v[10:11], v[10:11], v[38:39] op_sel_hi:[1,0]
	v_pk_mul_f32 v[8:9], v[8:9], v[38:39] op_sel_hi:[1,0]
	v_pk_mul_f32 v[6:7], v[6:7], v[38:39] op_sel_hi:[1,0]
	v_pk_mul_f32 v[4:5], v[4:5], v[38:39] op_sel_hi:[1,0]
	v_pk_mul_f32 v[2:3], v[2:3], v[38:39] op_sel_hi:[1,0]
	v_pk_mul_f32 v[32:33], v[32:33], v[38:39] op_sel_hi:[1,0]
	v_pk_mul_f32 v[30:31], v[30:31], v[38:39] op_sel_hi:[1,0]
	v_pk_mul_f32 v[28:29], v[28:29], v[38:39] op_sel_hi:[1,0]
	v_pk_mul_f32 v[26:27], v[26:27], v[38:39] op_sel_hi:[1,0]
	v_pk_mul_f32 v[24:25], v[24:25], v[38:39] op_sel_hi:[1,0]
	v_pk_mul_f32 v[22:23], v[22:23], v[38:39] op_sel_hi:[1,0]
	v_pk_mul_f32 v[20:21], v[20:21], v[38:39] op_sel_hi:[1,0]
	v_pk_mul_f32 v[18:19], v[18:19], v[38:39] op_sel_hi:[1,0]
	v_mul_f32_e32 v144, v144, v38
	v_mov_b32_e32 v35, v34
	v_mov_b32_e32 v36, v34
	v_mov_b32_e32 v37, v34
	v_mov_b32_e32 v38, v34
	v_mov_b32_e32 v39, v34
	v_mov_b32_e32 v40, v34
	v_mov_b32_e32 v41, v34
	v_mov_b32_e32 v42, v34
	v_mov_b32_e32 v43, v34
	v_mov_b32_e32 v44, v34
	v_mov_b32_e32 v45, v34
	v_mov_b32_e32 v46, v34
	v_mov_b32_e32 v47, v34
	v_mov_b32_e32 v48, v34
	v_mov_b32_e32 v49, v34
	v_mov_b32_e32 v50, v34
	v_mov_b32_e32 v51, v34
	v_mov_b32_e32 v52, v34
	v_mov_b32_e32 v53, v34
	v_mov_b32_e32 v54, v34
	v_mov_b32_e32 v55, v34
	v_mov_b32_e32 v56, v34
	v_mov_b32_e32 v57, v34
	v_mov_b32_e32 v58, v34
	v_mov_b32_e32 v59, v34
	v_mov_b32_e32 v60, v34
	v_mov_b32_e32 v61, v34
	v_mov_b32_e32 v62, v34
	v_mov_b32_e32 v63, v34
	v_mov_b32_e32 v64, v34
	v_mov_b32_e32 v65, v34

; #define LAS __attribute__((address_space(3)))
; __device__ __forceinline__ float max3f(float a, float b, float c) { float r; asm("v_max3_f32 %0, %1, %2, %3" : "=v"(r) : "v"(a), "v"(b), "v"(c)); return r; }
; template <int DQK, int DV, bool BIAS> ...
;     ...
;         const LAS unsigned char* kb = lds + buf * KBUF + r32 * KP + hi * 16;
; #pragma unroll
;         for (int ks = 0; ks < NKS; ++ks) {
;             const bf16x8 k0 = *(const LAS bf16x8*)(kb + ks * 32), k1 = *(const LAS bf16x8*)(kb + 32 * KP + ks * 32);
;             if (ks == 0) { p0 = __builtin_amdgcn_mfma_f32_32x32x16_bf16(k0, qf[0], negm, 0, 0, 0); p1 = __builtin_amdgcn_mfma_f32_32x32x16_bf16(k1, qf[0], negm, 0, 0, 0); }
;             else { p0 = __builtin_amdgcn_mfma_f32_32x32x16_bf16(k0, qf[ks], p0, 0, 0, 0); p1 = __builtin_amdgcn_mfma_f32_32x32x16_bf16(k1, qf[ks], p1, 0, 0, 0); }
;         }
;         if (BIAS) {
;             asm volatile("s_nop 15\n\ts_nop 7" : "+v"(p0), "+v"(p1));
;             const float d0 = qp - (float)(t * 64 + 4 * hi);
; #pragma unroll
;             for (int r = 0; r < 16; ++r) { const float dk = d0 - (float)((r & 3) + 8 * (r >> 2)); p0[r] = p0[r] - sl2 * fabsf(dk); p1[r] = p1[r] - sl2 * fabsf(dk - 32.f); }
;         } else {
;             asm volatile("s_nop 15\n\ts_nop 7" : "+v"(p0), "+v"(p1));
;         }
;         float mxa = max3f(p0[0], p0[1], p1[0]), mxb = max3f(p0[2], p0[3], p1[1]); mxa = max3f(mxa, p1[2], p1[3]);
; #pragma unroll
;         for (int r = 4; r < 16; r += 4) { mxa = max3f(mxa, p0[r], p0[r + 1]); mxb = max3f(mxb, p0[r + 2], p0[r + 3]); mxa = max3f(mxa, p1[r], p1[r + 1]); mxb = max3f(mxb, p1[r + 2], p1[r + 3]); }
;         float mx = fmaxf(mxa, mxb);
;         if (__any(mx > 8.f)) {
;             mx = fmaxf(mx, __shfl_xor(mx, 32));
;             const float dl = fmaxf(mx, 0.f); mhat += dl;
;             const float f = __builtin_amdgcn_exp2f(-dl);
; #pragma unroll
;             for (int r = 0; r < 16; ++r) { p0[r] -= dl; p1[r] -= dl; negm[r] = -mhat; }
;             l *= f;
; #pragma unroll
;             for (int d = 0; d < NDT; ++d)
; #pragma unroll
;                 for (int r = 0; r < 16; ++r) o[d][r] *= f;
;         }
.LBB0_612:
	v_add_f32_e32 v150, 0, v150
	v_add_f32_e32 v150, v151, v150
	ds_read_b128 v[66:69], v130 offset:18432
	ds_read_b128 v[180:183], v130 offset:18464
	v_add_f32_e32 v145, v145, v150
	ds_read_b128 v[184:187], v130 offset:23040
	ds_read_b128 v[188:191], v130 offset:23072
	v_add_f32_e32 v145, v147, v145
	v_add_f32_e32 v145, v148, v145
	v_add_f32_e32 v145, v149, v145
	s_waitcnt lgkmcnt(3)
	v_mfma_f32_32x32x16_bf16 v[82:97], v[66:69], v[98:101], v[34:49]
	v_add_f32_e32 v145, v152, v145
	v_add_f32_e32 v145, v153, v145
	v_add_f32_e32 v145, v155, v145
	v_add_f32_e32 v145, v156, v145
	v_add_f32_e32 v145, v157, v145
	v_add_f32_e32 v145, v158, v145
	v_add_f32_e32 v145, v159, v145
	s_waitcnt lgkmcnt(1)
	v_mfma_f32_32x32x16_bf16 v[66:81], v[184:187], v[98:101], v[34:49]
	ds_read_b128 v[148:151], v130 offset:18496
	v_add_f32_e32 v145, v154, v145
	v_add_f32_e32 v145, v160, v145
	v_add_f32_e32 v145, v161, v145
	v_add_f32_e32 v145, v165, v145
	v_add_f32_e32 v145, v166, v145
	v_add_f32_e32 v145, v167, v145
	v_mfma_f32_32x32x16_bf16 v[82:97], v[180:183], v[102:105], v[82:97]
	ds_read_b128 v[156:159], v130 offset:23104
	ds_read_b128 v[180:183], v130 offset:18528
	v_add_f32_e32 v145, v162, v145
	v_add_f32_e32 v145, v163, v145
	v_add_f32_e32 v145, v164, v145
	v_add_f32_e32 v145, v169, v145
	v_add_f32_e32 v145, v170, v145
	v_add_f32_e32 v145, v175, v145
	s_waitcnt lgkmcnt(3)
	v_mfma_f32_32x32x16_bf16 v[66:81], v[188:191], v[102:105], v[66:81]
	v_add_f32_e32 v145, v176, v145
	v_add_f32_e32 v145, v171, v145
	v_add_f32_e32 v145, v172, v145
	v_add_f32_e32 v145, v173, v145
	v_add_f32_e32 v145, v174, v145
	v_add_f32_e32 v145, v177, v145
	v_add_f32_e32 v145, v178, v145
	s_waitcnt lgkmcnt(2)
	v_mfma_f32_32x32x16_bf16 v[82:97], v[148:151], v[106:109], v[82:97]
	ds_read_b128 v[148:151], v130 offset:23136
	v_add_f32_e32 v144, v144, v145
	s_waitcnt lgkmcnt(2)
	v_mfma_f32_32x32x16_bf16 v[66:81], v[156:159], v[106:109], v[66:81]
	s_waitcnt lgkmcnt(1)
	v_mfma_f32_32x32x16_bf16 v[82:97], v[180:183], v[110:113], v[82:97]
	s_waitcnt lgkmcnt(0)
	v_mfma_f32_32x32x16_bf16 v[66:81], v[148:151], v[110:113], v[66:81]
	s_nop 15
	s_nop 7
	s_nop 0
	v_max3_f32 v145, v82, v83, v66
	v_max3_f32 v147, v84, v85, v67
	v_max3_f32 v145, v145, v68, v69
	v_max3_f32 v147, v147, v88, v89
	v_max3_f32 v145, v145, v86, v87
	v_max3_f32 v147, v147, v72, v73
	v_max3_f32 v145, v145, v70, v71
	v_max3_f32 v147, v147, v92, v93
	v_max3_f32 v145, v145, v90, v91
	v_max3_f32 v147, v147, v76, v77
	v_max3_f32 v145, v145, v74, v75
	v_max3_f32 v147, v147, v96, v97
	v_max3_f32 v145, v145, v94, v95
	v_max3_f32 v147, v147, v80, v81
	v_max3_f32 v145, v145, v78, v79
	v_max_f32_e32 v145, v145, v147
	v_cmp_lt_f32_e32 vcc, s47, v145
	s_cbranch_vccz .LBB0_614
	ds_bpermute_b32 v34, v168, v145
	s_waitcnt lgkmcnt(0)
	v_max3_f32 v36, v145, v34, 0
	v_exp_f32_e64 v38, -v36
	v_add_f32_e32 v143, v143, v36
	v_xor_b32_e32 v34, 0x80000000, v143
	v_pk_add_f32 v[82:83], v[82:83], v[36:37] op_sel_hi:[1,0] neg_lo:[0,1] neg_hi:[0,1]
	v_pk_add_f32 v[66:67], v[66:67], v[36:37] op_sel_hi:[1,0] neg_lo:[0,1] neg_hi:[0,1]
	v_pk_add_f32 v[84:85], v[84:85], v[36:37] op_sel_hi:[1,0] neg_lo:[0,1] neg_hi:[0,1]
	v_pk_add_f32 v[68:69], v[68:69], v[36:37] op_sel_hi:[1,0] neg_lo:[0,1] neg_hi:[0,1]
	v_pk_add_f32 v[86:87], v[86:87], v[36:37] op_sel_hi:[1,0] neg_lo:[0,1] neg_hi:[0,1]
	v_pk_add_f32 v[70:71], v[70:71], v[36:37] op_sel_hi:[1,0] neg_lo:[0,1] neg_hi:[0,1]
	v_pk_add_f32 v[88:89], v[88:89], v[36:37] op_sel_hi:[1,0] neg_lo:[0,1] neg_hi:[0,1]
	v_pk_add_f32 v[72:73], v[72:73], v[36:37] op_sel_hi:[1,0] neg_lo:[0,1] neg_hi:[0,1]
	v_pk_add_f32 v[90:91], v[90:91], v[36:37] op_sel_hi:[1,0] neg_lo:[0,1] neg_hi:[0,1]
	v_pk_add_f32 v[74:75], v[74:75], v[36:37] op_sel_hi:[1,0] neg_lo:[0,1] neg_hi:[0,1]
	v_pk_add_f32 v[92:93], v[92:93], v[36:37] op_sel_hi:[1,0] neg_lo:[0,1] neg_hi:[0,1]
	v_pk_add_f32 v[76:77], v[76:77], v[36:37] op_sel_hi:[1,0] neg_lo:[0,1] neg_hi:[0,1]
	v_pk_add_f32 v[94:95], v[94:95], v[36:37] op_sel_hi:[1,0] neg_lo:[0,1] neg_hi:[0,1]
	v_pk_add_f32 v[78:79], v[78:79], v[36:37] op_sel_hi:[1,0] neg_lo:[0,1] neg_hi:[0,1]
	v_pk_add_f32 v[96:97], v[96:97], v[36:37] op_sel_hi:[1,0] neg_lo:[0,1] neg_hi:[0,1]
	v_pk_add_f32 v[80:81], v[80:81], v[36:37] op_sel_hi:[1,0] neg_lo:[0,1] neg_hi:[0,1]
	v_pk_mul_f32 v[16:17], v[16:17], v[38:39] op_sel_hi:[1,0]
	v_pk_mul_f32 v[14:15], v[14:15], v[38:39] op_sel_hi:[1,0]
	v_pk_mul_f32 v[12:13], v[12:13], v[38:39] op_sel_hi:[1,0]
	v_pk_mul_f32 v[10:11], v[10:11], v[38:39] op_sel_hi:[1,0]
	v_pk_mul_f32 v[8:9], v[8:9], v[38:39] op_sel_hi:[1,0]
	v_pk_mul_f32 v[6:7], v[6:7], v[38:39] op_sel_hi:[1,0]
	v_pk_mul_f32 v[4:5], v[4:5], v[38:39] op_sel_hi:[1,0]
	v_pk_mul_f32 v[2:3], v[2:3], v[38:39] op_sel_hi:[1,0]
	v_pk_mul_f32 v[32:33], v[32:33], v[38:39] op_sel_hi:[1,0]
	v_pk_mul_f32 v[30:31], v[30:31], v[38:39] op_sel_hi:[1,0]
	v_pk_mul_f32 v[28:29], v[28:29], v[38:39] op_sel_hi:[1,0]
	v_pk_mul_f32 v[26:27], v[26:27], v[38:39] op_sel_hi:[1,0]
	v_pk_mul_f32 v[24:25], v[24:25], v[38:39] op_sel_hi:[1,0]
	v_pk_mul_f32 v[22:23], v[22:23], v[38:39] op_sel_hi:[1,0]
	v_pk_mul_f32 v[20:21], v[20:21], v[38:39] op_sel_hi:[1,0]
	v_pk_mul_f32 v[18:19], v[18:19], v[38:39] op_sel_hi:[1,0]
	v_mul_f32_e32 v144, v144, v38
	v_mov_b32_e32 v35, v34
	v_mov_b32_e32 v36, v34
	v_mov_b32_e32 v37, v34
	v_mov_b32_e32 v38, v34
	v_mov_b32_e32 v39, v34
	v_mov_b32_e32 v40, v34
	v_mov_b32_e32 v41, v34
	v_mov_b32_e32 v42, v34
	v_mov_b32_e32 v43, v34
	v_mov_b32_e32 v44, v34
	v_mov_b32_e32 v45, v34
	v_mov_b32_e32 v46, v34
	v_mov_b32_e32 v47, v34
	v_mov_b32_e32 v48, v34
	v_mov_b32_e32 v49, v34
	v_mov_b32_e32 v50, v34
	v_mov_b32_e32 v51, v34
	v_mov_b32_e32 v52, v34
	v_mov_b32_e32 v53, v34
	v_mov_b32_e32 v54, v34
	v_mov_b32_e32 v55, v34
	v_mov_b32_e32 v56, v34
	v_mov_b32_e32 v57, v34
	v_mov_b32_e32 v58, v34
	v_mov_b32_e32 v59, v34
	v_mov_b32_e32 v60, v34
	v_mov_b32_e32 v61, v34
	v_mov_b32_e32 v62, v34
	v_mov_b32_e32 v63, v34
	v_mov_b32_e32 v64, v34
	v_mov_b32_e32 v65, v34
; #define LAS __attribute__((address_space(3)))
; template <int DQK, int DV, bool BIAS> ...
;     ...
;         const LAS unsigned char* kb = lds + buf * KBUF + r32 * KP + hi * 16;
; #pragma unroll
;         for (int ks = 0; ks < NKS; ++ks) {
;             const bf16x8 k0 = *(const LAS bf16x8*)(kb + ks * 32), k1 = *(const LAS bf16x8*)(kb + 32 * KP + ks * 32);
;             if (ks == 0) { p0 = __builtin_amdgcn_mfma_f32_32x32x16_bf16(k0, qf[0], negm, 0, 0, 0); p1 = __builtin_amdgcn_mfma_f32_32x32x16_bf16(k1, qf[0], negm, 0, 0, 0); }
;             else { p0 = __builtin_amdgcn_mfma_f32_32x32x16_bf16(k0, qf[ks], p0, 0, 0, 0); p1 = __builtin_amdgcn_mfma_f32_32x32x16_bf16(k1, qf[ks], p1, 0, 0, 0); }
;         }
;         if (BIAS) {
;             asm volatile("s_nop 15\n\ts_nop 7" : "+v"(p0), "+v"(p1));
;             const float d0 = qp - (float)(t * 64 + 4 * hi);
; #pragma unroll
;             for (int r = 0; r < 16; ++r) { const float dk = d0 - (float)((r & 3) + 8 * (r >> 2)); p0[r] = p0[r] - sl2 * fabsf(dk); p1[r] = p1[r] - sl2 * fabsf(dk - 32.f); }
;         } else {
;             asm volatile("s_nop 15\n\ts_nop 7" : "+v"(p0), "+v"(p1));
;         }
;     ...
;             const LAS unsigned char* vbase = lds + VOFF + vcur * VBUF + (4 * hi + ((lane & 15) >> 2)) * 64 + ((lane >> 4) & 1) * 32 + (lane & 3) * 8;
;             float ls = 0.f;
; #pragma unroll
;             for (int hs = 0; hs < 4; ++hs) {
;                 float e[8];
; #pragma unroll
;                 for (int j = 0; j < 8; ++j) { e[j] = __builtin_amdgcn_exp2f(hs < 2 ? p0[8 * (hs & 1) + j] : p1[8 * (hs & 1) + j]); ls += e[j]; }
;                 pw[hs].x = cvtpk(e[0], e[1]); pw[hs].y = cvtpk(e[2], e[3]); pw[hs].z = cvtpk(e[4], e[5]); pw[hs].w = cvtpk(e[6], e[7]);
;                 const bf16x8 pbv = __builtin_bit_cast(bf16x8, pw[hs]);
; #pragma unroll
;                 for (int d = 0; d < NDT; ++d) { const LAS unsigned char* vp = vbase + d * 4096 + hs * 1024;
;                     const v4i16_t a0 = __builtin_amdgcn_ds_read_tr16_b64_v4i16((LAS v4i16_t*)vp), a1 = __builtin_amdgcn_ds_read_tr16_b64_v4i16((LAS v4i16_t*)(vp + 512));
;                     const bf16x8 av = {a0[0], a0[1], a0[2], a0[3], a1[0], a1[1], a1[2], a1[3]};
;                     o[d] = __builtin_amdgcn_mfma_f32_32x32x16_bf16(av, pbv, o[d], 0, 0, 0); }
;                 __builtin_amdgcn_sched_barrier(0);
;             }
;             l += ls;
.LBB0_614:
	v_exp_f32_e32 v145, v82
	v_exp_f32_e32 v147, v83
	v_exp_f32_e32 v152, v84
	v_exp_f32_e32 v153, v85
	v_exp_f32_e32 v154, v86
	v_exp_f32_e32 v155, v87
	ds_read_b64_tr_b16 v[82:83], v141 offset:53248
	ds_read_b64_tr_b16 v[84:85], v141 offset:53760
	v_exp_f32_e32 v156, v88
	v_exp_f32_e32 v157, v89
	ds_read_b64_tr_b16 v[148:149], v141 offset:57344
	ds_read_b64_tr_b16 v[150:151], v141 offset:57856
	v_cvt_pk_bf16_f32 v86, v145, v147
	v_cvt_pk_bf16_f32 v87, v152, v153
	v_cvt_pk_bf16_f32 v88, v154, v155
	v_cvt_pk_bf16_f32 v89, v156, v157
	s_waitcnt lgkmcnt(2)
	s_nop 0
	v_mfma_f32_32x32x16_bf16 v[18:33], v[82:85], v[86:89], v[18:33]
	v_add_f32_e32 v82, 0, v145
	v_add_f32_e32 v82, v147, v82
	v_add_f32_e32 v82, v152, v82
	v_add_f32_e32 v82, v153, v82
	v_add_f32_e32 v82, v154, v82
	v_add_f32_e32 v82, v155, v82
	v_add_f32_e32 v82, v156, v82
	s_waitcnt lgkmcnt(0)
	v_mfma_f32_32x32x16_bf16 v[2:17], v[148:151], v[86:89], v[2:17]
	v_add_f32_e32 v145, v157, v82
	v_exp_f32_e32 v147, v90
	v_exp_f32_e32 v148, v91
	v_exp_f32_e32 v149, v92
	v_exp_f32_e32 v150, v93
	v_exp_f32_e32 v94, v94
	v_exp_f32_e32 v95, v95
	ds_read_b64_tr_b16 v[82:83], v141 offset:54272
	ds_read_b64_tr_b16 v[84:85], v141 offset:54784
	v_exp_f32_e32 v96, v96
	v_exp_f32_e32 v97, v97
	ds_read_b64_tr_b16 v[90:91], v141 offset:58368
	ds_read_b64_tr_b16 v[92:93], v141 offset:58880
	v_cvt_pk_bf16_f32 v86, v147, v148
	v_cvt_pk_bf16_f32 v87, v149, v150
	v_cvt_pk_bf16_f32 v88, v94, v95
	v_cvt_pk_bf16_f32 v89, v96, v97
	s_waitcnt lgkmcnt(2)
	s_nop 0
	v_mfma_f32_32x32x16_bf16 v[18:33], v[82:85], v[86:89], v[18:33]
	v_add_f32_e32 v82, v147, v145
	v_add_f32_e32 v82, v148, v82
	v_add_f32_e32 v82, v149, v82
	v_add_f32_e32 v82, v150, v82
	v_add_f32_e32 v82, v94, v82
	v_add_f32_e32 v82, v95, v82
	v_add_f32_e32 v82, v96, v82
	s_waitcnt lgkmcnt(0)
	v_mfma_f32_32x32x16_bf16 v[2:17], v[90:93], v[86:89], v[2:17]
	v_add_f32_e32 v86, v97, v82
	v_exp_f32_e32 v87, v66
	v_exp_f32_e32 v88, v67
	v_exp_f32_e32 v89, v68
	v_exp_f32_e32 v90, v69
	v_exp_f32_e32 v91, v70
	v_exp_f32_e32 v92, v71
	ds_read_b64_tr_b16 v[66:67], v141 offset:55296
	ds_read_b64_tr_b16 v[68:69], v141 offset:55808
	v_exp_f32_e32 v93, v72
	v_exp_f32_e32 v94, v73
	ds_read_b64_tr_b16 v[82:83], v141 offset:59392
	ds_read_b64_tr_b16 v[84:85], v141 offset:59904
	v_cvt_pk_bf16_f32 v70, v87, v88
	v_cvt_pk_bf16_f32 v71, v89, v90
	v_cvt_pk_bf16_f32 v72, v91, v92
	v_cvt_pk_bf16_f32 v73, v93, v94
	s_waitcnt lgkmcnt(2)
	s_nop 0
	v_mfma_f32_32x32x16_bf16 v[18:33], v[66:69], v[70:73], v[18:33]
	v_add_f32_e32 v66, v87, v86
	v_add_f32_e32 v66, v88, v66
	v_add_f32_e32 v66, v89, v66
	v_add_f32_e32 v66, v90, v66
	v_add_f32_e32 v66, v91, v66
	v_add_f32_e32 v66, v92, v66
	v_add_f32_e32 v66, v93, v66
	s_waitcnt lgkmcnt(0)
	v_mfma_f32_32x32x16_bf16 v[2:17], v[82:85], v[70:73], v[2:17]
	v_add_f32_e32 v82, v94, v66
	v_exp_f32_e32 v83, v74
	v_exp_f32_e32 v84, v75
	v_exp_f32_e32 v85, v76
	v_exp_f32_e32 v86, v77
	v_exp_f32_e32 v78, v78
	v_exp_f32_e32 v79, v79
	ds_read_b64_tr_b16 v[66:67], v141 offset:56320
	ds_read_b64_tr_b16 v[68:69], v141 offset:56832
	v_exp_f32_e32 v80, v80
	v_exp_f32_e32 v81, v81
	ds_read_b64_tr_b16 v[74:75], v141 offset:60416
	ds_read_b64_tr_b16 v[76:77], v141 offset:60928
	v_cvt_pk_bf16_f32 v70, v83, v84
	v_cvt_pk_bf16_f32 v71, v85, v86
	v_cvt_pk_bf16_f32 v72, v78, v79
	v_cvt_pk_bf16_f32 v73, v80, v81
	s_waitcnt lgkmcnt(2)
	s_nop 0
	v_mfma_f32_32x32x16_bf16 v[18:33], v[66:69], v[70:73], v[18:33]
	v_add_f32_e32 v66, v83, v82
	v_add_f32_e32 v66, v84, v66
	v_add_f32_e32 v66, v85, v66
	v_add_f32_e32 v66, v86, v66
	v_add_f32_e32 v66, v78, v66
	v_add_f32_e32 v66, v79, v66
	v_add_f32_e32 v66, v80, v66
	s_waitcnt lgkmcnt(0)
	v_mfma_f32_32x32x16_bf16 v[2:17], v[74:77], v[70:73], v[2:17]
	v_add_f32_e32 v94, v81, v66
	ds_read_b128 v[82:85], v130 offset:27648
	ds_read_b128 v[86:89], v130 offset:27680
	s_waitcnt lgkmcnt(1)
	v_mfma_f32_32x32x16_bf16 v[66:81], v[82:85], v[98:101], v[34:49]
	ds_read_b128 v[82:85], v130 offset:32256
	ds_read_b128 v[90:93], v130 offset:32288
	s_waitcnt lgkmcnt(1)
	v_mfma_f32_32x32x16_bf16 v[34:49], v[82:85], v[98:101], v[34:49]
	v_mfma_f32_32x32x16_bf16 v[66:81], v[86:89], v[102:105], v[66:81]
	ds_read_b128 v[82:85], v130 offset:27712
	ds_read_b128 v[86:89], v130 offset:27744
	s_waitcnt lgkmcnt(2)
	v_mfma_f32_32x32x16_bf16 v[34:49], v[90:93], v[102:105], v[34:49]
	s_waitcnt lgkmcnt(1)
	v_mfma_f32_32x32x16_bf16 v[66:81], v[82:85], v[106:109], v[66:81]
	ds_read_b128 v[82:85], v130 offset:32320
	ds_read_b128 v[90:93], v130 offset:32352
	s_waitcnt lgkmcnt(1)
	v_mfma_f32_32x32x16_bf16 v[34:49], v[82:85], v[106:109], v[34:49]
	v_add_f32_e32 v82, v144, v94
	v_mfma_f32_32x32x16_bf16 v[66:81], v[86:89], v[110:113], v[66:81]
	s_waitcnt lgkmcnt(0)
	v_mfma_f32_32x32x16_bf16 v[34:49], v[90:93], v[110:113], v[34:49]
	s_nop 15
	s_nop 7
	s_nop 0
	v_max3_f32 v83, v66, v67, v34
	v_max3_f32 v84, v68, v69, v35
	v_max3_f32 v83, v83, v36, v37
	v_max3_f32 v84, v84, v72, v73
	v_max3_f32 v83, v83, v70, v71
	v_max3_f32 v84, v84, v40, v41
	v_max3_f32 v83, v83, v38, v39
	v_max3_f32 v84, v84, v76, v77
	v_max3_f32 v83, v83, v74, v75
	v_max3_f32 v84, v84, v44, v45
	v_max3_f32 v83, v83, v42, v43
	v_max3_f32 v84, v84, v80, v81
	v_max3_f32 v83, v83, v78, v79
	v_max3_f32 v84, v84, v48, v49
	v_max3_f32 v83, v83, v46, v47
	v_max_f32_e32 v83, v83, v84
	v_cmp_lt_f32_e32 vcc, s47, v83
	s_cbranch_vccz .LBB0_601
; template <int DQK, int DV, bool BIAS> ...
;     ...
;         if (__any(mx > 8.f)) {
;             mx = fmaxf(mx, __shfl_xor(mx, 32));
;             const float dl = fmaxf(mx, 0.f); mhat += dl;
;             const float f = __builtin_amdgcn_exp2f(-dl);
; #pragma unroll
;             for (int r = 0; r < 16; ++r) { p0[r] -= dl; p1[r] -= dl; negm[r] = -mhat; }
;             l *= f;
; #pragma unroll
;             for (int d = 0; d < NDT; ++d)
; #pragma unroll
;                 for (int r = 0; r < 16; ++r) o[d][r] *= f;
;         }
	ds_bpermute_b32 v50, v168, v83
	s_waitcnt lgkmcnt(0)
	v_max3_f32 v52, v83, v50, 0
	v_exp_f32_e64 v54, -v52
	v_add_f32_e32 v143, v143, v52
	v_xor_b32_e32 v50, 0x80000000, v143
	v_pk_add_f32 v[66:67], v[66:67], v[52:53] op_sel_hi:[1,0] neg_lo:[0,1] neg_hi:[0,1]
	v_pk_add_f32 v[34:35], v[34:35], v[52:53] op_sel_hi:[1,0] neg_lo:[0,1] neg_hi:[0,1]
	v_pk_add_f32 v[68:69], v[68:69], v[52:53] op_sel_hi:[1,0] neg_lo:[0,1] neg_hi:[0,1]
	v_pk_add_f32 v[36:37], v[36:37], v[52:53] op_sel_hi:[1,0] neg_lo:[0,1] neg_hi:[0,1]
	v_pk_add_f32 v[70:71], v[70:71], v[52:53] op_sel_hi:[1,0] neg_lo:[0,1] neg_hi:[0,1]
	v_pk_add_f32 v[38:39], v[38:39], v[52:53] op_sel_hi:[1,0] neg_lo:[0,1] neg_hi:[0,1]
	v_pk_add_f32 v[72:73], v[72:73], v[52:53] op_sel_hi:[1,0] neg_lo:[0,1] neg_hi:[0,1]
	v_pk_add_f32 v[40:41], v[40:41], v[52:53] op_sel_hi:[1,0] neg_lo:[0,1] neg_hi:[0,1]
	v_pk_add_f32 v[74:75], v[74:75], v[52:53] op_sel_hi:[1,0] neg_lo:[0,1] neg_hi:[0,1]
	v_pk_add_f32 v[42:43], v[42:43], v[52:53] op_sel_hi:[1,0] neg_lo:[0,1] neg_hi:[0,1]
	v_pk_add_f32 v[76:77], v[76:77], v[52:53] op_sel_hi:[1,0] neg_lo:[0,1] neg_hi:[0,1]
	v_pk_add_f32 v[44:45], v[44:45], v[52:53] op_sel_hi:[1,0] neg_lo:[0,1] neg_hi:[0,1]
	v_pk_add_f32 v[78:79], v[78:79], v[52:53] op_sel_hi:[1,0] neg_lo:[0,1] neg_hi:[0,1]
	v_pk_add_f32 v[46:47], v[46:47], v[52:53] op_sel_hi:[1,0] neg_lo:[0,1] neg_hi:[0,1]
	v_pk_add_f32 v[80:81], v[80:81], v[52:53] op_sel_hi:[1,0] neg_lo:[0,1] neg_hi:[0,1]
	v_pk_add_f32 v[48:49], v[48:49], v[52:53] op_sel_hi:[1,0] neg_lo:[0,1] neg_hi:[0,1]
	v_pk_mul_f32 v[16:17], v[16:17], v[54:55] op_sel_hi:[1,0]
	v_pk_mul_f32 v[14:15], v[14:15], v[54:55] op_sel_hi:[1,0]
	v_pk_mul_f32 v[12:13], v[12:13], v[54:55] op_sel_hi:[1,0]
	v_pk_mul_f32 v[10:11], v[10:11], v[54:55] op_sel_hi:[1,0]
	v_pk_mul_f32 v[8:9], v[8:9], v[54:55] op_sel_hi:[1,0]
	v_pk_mul_f32 v[6:7], v[6:7], v[54:55] op_sel_hi:[1,0]
	v_pk_mul_f32 v[4:5], v[4:5], v[54:55] op_sel_hi:[1,0]
	v_pk_mul_f32 v[2:3], v[2:3], v[54:55] op_sel_hi:[1,0]
	v_pk_mul_f32 v[32:33], v[32:33], v[54:55] op_sel_hi:[1,0]
	v_pk_mul_f32 v[30:31], v[30:31], v[54:55] op_sel_hi:[1,0]
	v_pk_mul_f32 v[28:29], v[28:29], v[54:55] op_sel_hi:[1,0]
	v_pk_mul_f32 v[26:27], v[26:27], v[54:55] op_sel_hi:[1,0]
	v_pk_mul_f32 v[24:25], v[24:25], v[54:55] op_sel_hi:[1,0]
	v_pk_mul_f32 v[22:23], v[22:23], v[54:55] op_sel_hi:[1,0]
	v_pk_mul_f32 v[20:21], v[20:21], v[54:55] op_sel_hi:[1,0]
	v_pk_mul_f32 v[18:19], v[18:19], v[54:55] op_sel_hi:[1,0]
	v_mul_f32_e32 v82, v82, v54
	v_mov_b32_e32 v51, v50
	v_mov_b32_e32 v52, v50
	v_mov_b32_e32 v53, v50
	v_mov_b32_e32 v54, v50
	v_mov_b32_e32 v55, v50
	v_mov_b32_e32 v56, v50
	v_mov_b32_e32 v57, v50
	v_mov_b32_e32 v58, v50
	v_mov_b32_e32 v59, v50
	v_mov_b32_e32 v60, v50
	v_mov_b32_e32 v61, v50
	v_mov_b32_e32 v62, v50
	v_mov_b32_e32 v63, v50
	v_mov_b32_e32 v64, v50
	v_mov_b32_e32 v65, v50
	s_branch .LBB0_601

; #define LAS __attribute__((address_space(3)))
; __device__ __forceinline__ float max3f(float a, float b, float c) { float r; asm("v_max3_f32 %0, %1, %2, %3" : "=v"(r) : "v"(a), "v"(b), "v"(c)); return r; }
; template <int DQK, int DV, bool BIAS> ...
;     ...
;         const LAS unsigned char* kb = lds + buf * KBUF + r32 * KP + hi * 16;
; #pragma unroll
;         for (int ks = 0; ks < NKS; ++ks) {
;             const bf16x8 k0 = *(const LAS bf16x8*)(kb + ks * 32), k1 = *(const LAS bf16x8*)(kb + 32 * KP + ks * 32);
;             if (ks == 0) { p0 = __builtin_amdgcn_mfma_f32_32x32x16_bf16(k0, qf[0], negm, 0, 0, 0); p1 = __builtin_amdgcn_mfma_f32_32x32x16_bf16(k1, qf[0], negm, 0, 0, 0); }
;             else { p0 = __builtin_amdgcn_mfma_f32_32x32x16_bf16(k0, qf[ks], p0, 0, 0, 0); p1 = __builtin_amdgcn_mfma_f32_32x32x16_bf16(k1, qf[ks], p1, 0, 0, 0); }
;         }
;         if (BIAS) {
;             asm volatile("s_nop 15\n\ts_nop 7" : "+v"(p0), "+v"(p1));
;             const float d0 = qp - (float)(t * 64 + 4 * hi);
; #pragma unroll
;             for (int r = 0; r < 16; ++r) { const float dk = d0 - (float)((r & 3) + 8 * (r >> 2)); p0[r] = p0[r] - sl2 * fabsf(dk); p1[r] = p1[r] - sl2 * fabsf(dk - 32.f); }
;         } else {
;             asm volatile("s_nop 15\n\ts_nop 7" : "+v"(p0), "+v"(p1));
;         }
;         float mxa = max3f(p0[0], p0[1], p1[0]), mxb = max3f(p0[2], p0[3], p1[1]); mxa = max3f(mxa, p1[2], p1[3]);
; #pragma unroll
;         for (int r = 4; r < 16; r += 4) { mxa = max3f(mxa, p0[r], p0[r + 1]); mxb = max3f(mxb, p0[r + 2], p0[r + 3]); mxa = max3f(mxa, p1[r], p1[r + 1]); mxb = max3f(mxb, p1[r + 2], p1[r + 3]); }
;         float mx = fmaxf(mxa, mxb);
;         if (__any(mx > 8.f)) {
;             mx = fmaxf(mx, __shfl_xor(mx, 32));
;             const float dl = fmaxf(mx, 0.f); mhat += dl;
;             const float f = __builtin_amdgcn_exp2f(-dl);
; #pragma unroll
;             for (int r = 0; r < 16; ++r) { p0[r] -= dl; p1[r] -= dl; negm[r] = -mhat; }
;             l *= f;
; #pragma unroll
;             for (int d = 0; d < NDT; ++d)
; #pragma unroll
;                 for (int r = 0; r < 16; ++r) o[d][r] *= f;
;         }
.LBB0_642:
	ds_read_b128 v[34:37], v148
	ds_read_b128 v[38:41], v148 offset:32
	s_waitcnt lgkmcnt(1)
	v_mfma_f32_32x32x16_bf16 v[82:97], v[34:37], v[98:101], v[50:65]
	ds_read_b128 v[34:37], v148 offset:6656
	ds_read_b128 v[42:45], v148 offset:6688
	s_waitcnt lgkmcnt(1)
	v_mfma_f32_32x32x16_bf16 v[66:81], v[34:37], v[98:101], v[50:65]
	v_mfma_f32_32x32x16_bf16 v[82:97], v[38:41], v[102:105], v[82:97]
	ds_read_b128 v[34:37], v148 offset:64
	ds_read_b128 v[38:41], v148 offset:96
	s_waitcnt lgkmcnt(2)
	v_mfma_f32_32x32x16_bf16 v[66:81], v[42:45], v[102:105], v[66:81]
	s_waitcnt lgkmcnt(1)
	v_mfma_f32_32x32x16_bf16 v[82:97], v[34:37], v[106:109], v[82:97]
	ds_read_b128 v[34:37], v148 offset:6720
	ds_read_b128 v[42:45], v148 offset:6752
	s_waitcnt lgkmcnt(1)
	v_mfma_f32_32x32x16_bf16 v[66:81], v[34:37], v[106:109], v[66:81]
	v_mfma_f32_32x32x16_bf16 v[82:97], v[38:41], v[110:113], v[82:97]
	ds_read_b128 v[34:37], v148 offset:128
	ds_read_b128 v[38:41], v148 offset:160
	s_waitcnt lgkmcnt(2)
	v_mfma_f32_32x32x16_bf16 v[66:81], v[42:45], v[110:113], v[66:81]
	s_waitcnt lgkmcnt(1)
	v_mfma_f32_32x32x16_bf16 v[82:97], v[34:37], v[114:117], v[82:97]
	ds_read_b128 v[34:37], v148 offset:6784
	ds_read_b128 v[42:45], v148 offset:6816
	s_waitcnt lgkmcnt(1)
	v_mfma_f32_32x32x16_bf16 v[66:81], v[34:37], v[114:117], v[66:81]
	v_mfma_f32_32x32x16_bf16 v[82:97], v[38:41], v[118:121], v[82:97]
	s_waitcnt lgkmcnt(0)
	v_mfma_f32_32x32x16_bf16 v[66:81], v[42:45], v[118:121], v[66:81]
	s_nop 15
	s_nop 7
	s_nop 0
	v_max3_f32 v34, v82, v83, v66
	v_max3_f32 v35, v84, v85, v67
	v_max3_f32 v34, v34, v68, v69
	v_max3_f32 v35, v35, v88, v89
	v_max3_f32 v34, v34, v86, v87
	v_max3_f32 v35, v35, v72, v73
	v_max3_f32 v34, v34, v70, v71
	v_max3_f32 v35, v35, v92, v93
	v_max3_f32 v34, v34, v90, v91
	v_max3_f32 v35, v35, v76, v77
	v_max3_f32 v34, v34, v74, v75
	v_max3_f32 v35, v35, v96, v97
	v_max3_f32 v34, v34, v94, v95
	v_max3_f32 v35, v35, v80, v81
	v_max3_f32 v34, v34, v78, v79
	v_max_f32_e32 v34, v34, v35
	v_cmp_lt_f32_e32 vcc, s59, v34
	s_cbranch_vccz .LBB0_644
	ds_bpermute_b32 v35, v168, v34
	s_waitcnt lgkmcnt(0)
	v_max3_f32 v36, v34, v35, 0
	v_exp_f32_e64 v38, -v36
	v_add_f32_e32 v153, v153, v36
	v_xor_b32_e32 v34, 0x80000000, v153
	v_pk_add_f32 v[82:83], v[82:83], v[36:37] op_sel_hi:[1,0] neg_lo:[0,1] neg_hi:[0,1]
	v_pk_add_f32 v[66:67], v[66:67], v[36:37] op_sel_hi:[1,0] neg_lo:[0,1] neg_hi:[0,1]
	v_pk_add_f32 v[84:85], v[84:85], v[36:37] op_sel_hi:[1,0] neg_lo:[0,1] neg_hi:[0,1]
	v_pk_add_f32 v[68:69], v[68:69], v[36:37] op_sel_hi:[1,0] neg_lo:[0,1] neg_hi:[0,1]
	v_pk_add_f32 v[86:87], v[86:87], v[36:37] op_sel_hi:[1,0] neg_lo:[0,1] neg_hi:[0,1]
	v_pk_add_f32 v[70:71], v[70:71], v[36:37] op_sel_hi:[1,0] neg_lo:[0,1] neg_hi:[0,1]
	v_pk_add_f32 v[88:89], v[88:89], v[36:37] op_sel_hi:[1,0] neg_lo:[0,1] neg_hi:[0,1]
	v_pk_add_f32 v[72:73], v[72:73], v[36:37] op_sel_hi:[1,0] neg_lo:[0,1] neg_hi:[0,1]
	v_pk_add_f32 v[90:91], v[90:91], v[36:37] op_sel_hi:[1,0] neg_lo:[0,1] neg_hi:[0,1]
	v_pk_add_f32 v[74:75], v[74:75], v[36:37] op_sel_hi:[1,0] neg_lo:[0,1] neg_hi:[0,1]
	v_pk_add_f32 v[92:93], v[92:93], v[36:37] op_sel_hi:[1,0] neg_lo:[0,1] neg_hi:[0,1]
	v_pk_add_f32 v[76:77], v[76:77], v[36:37] op_sel_hi:[1,0] neg_lo:[0,1] neg_hi:[0,1]
	v_pk_add_f32 v[94:95], v[94:95], v[36:37] op_sel_hi:[1,0] neg_lo:[0,1] neg_hi:[0,1]
	v_pk_add_f32 v[78:79], v[78:79], v[36:37] op_sel_hi:[1,0] neg_lo:[0,1] neg_hi:[0,1]
	v_pk_add_f32 v[96:97], v[96:97], v[36:37] op_sel_hi:[1,0] neg_lo:[0,1] neg_hi:[0,1]
	v_pk_add_f32 v[80:81], v[80:81], v[36:37] op_sel_hi:[1,0] neg_lo:[0,1] neg_hi:[0,1]
	v_pk_mul_f32 v[32:33], v[32:33], v[38:39] op_sel_hi:[1,0]
	v_pk_mul_f32 v[30:31], v[30:31], v[38:39] op_sel_hi:[1,0]
	v_pk_mul_f32 v[28:29], v[28:29], v[38:39] op_sel_hi:[1,0]
	v_pk_mul_f32 v[26:27], v[26:27], v[38:39] op_sel_hi:[1,0]
	v_pk_mul_f32 v[24:25], v[24:25], v[38:39] op_sel_hi:[1,0]
	v_pk_mul_f32 v[22:23], v[22:23], v[38:39] op_sel_hi:[1,0]
	v_pk_mul_f32 v[20:21], v[20:21], v[38:39] op_sel_hi:[1,0]
	v_pk_mul_f32 v[18:19], v[18:19], v[38:39] op_sel_hi:[1,0]
	v_pk_mul_f32 v[16:17], v[16:17], v[38:39] op_sel_hi:[1,0]
	v_pk_mul_f32 v[14:15], v[14:15], v[38:39] op_sel_hi:[1,0]
	v_pk_mul_f32 v[12:13], v[12:13], v[38:39] op_sel_hi:[1,0]
	v_pk_mul_f32 v[10:11], v[10:11], v[38:39] op_sel_hi:[1,0]
	v_pk_mul_f32 v[8:9], v[8:9], v[38:39] op_sel_hi:[1,0]
	v_pk_mul_f32 v[6:7], v[6:7], v[38:39] op_sel_hi:[1,0]
	v_pk_mul_f32 v[4:5], v[4:5], v[38:39] op_sel_hi:[1,0]
	v_pk_mul_f32 v[2:3], v[2:3], v[38:39] op_sel_hi:[1,0]
	v_mul_f32_e32 v164, v164, v38
	v_mov_b32_e32 v35, v34
	v_mov_b32_e32 v36, v34
	v_mov_b32_e32 v37, v34
	v_mov_b32_e32 v38, v34
	v_mov_b32_e32 v39, v34
	v_mov_b32_e32 v40, v34
	v_mov_b32_e32 v41, v34
	v_mov_b32_e32 v42, v34
	v_mov_b32_e32 v43, v34
	v_mov_b32_e32 v44, v34
	v_mov_b32_e32 v45, v34
	v_mov_b32_e32 v46, v34
	v_mov_b32_e32 v47, v34
	v_mov_b32_e32 v48, v34
	v_mov_b32_e32 v49, v34
	v_mov_b32_e32 v50, v34
	v_mov_b32_e32 v51, v34
	v_mov_b32_e32 v52, v34
	v_mov_b32_e32 v53, v34
	v_mov_b32_e32 v54, v34
	v_mov_b32_e32 v55, v34
	v_mov_b32_e32 v56, v34
	v_mov_b32_e32 v57, v34
	v_mov_b32_e32 v58, v34
	v_mov_b32_e32 v59, v34
	v_mov_b32_e32 v60, v34
	v_mov_b32_e32 v61, v34
	v_mov_b32_e32 v62, v34
	v_mov_b32_e32 v63, v34
	v_mov_b32_e32 v64, v34
	v_mov_b32_e32 v65, v34
	s_branch .LBB0_645

; #define LAS __attribute__((address_space(3)))
; template <int DQK, int DV, bool BIAS> ...
;     ...
;         const LAS unsigned char* kb = lds + buf * KBUF + r32 * KP + hi * 16;
; #pragma unroll
;         for (int ks = 0; ks < NKS; ++ks) {
;             const bf16x8 k0 = *(const LAS bf16x8*)(kb + ks * 32), k1 = *(const LAS bf16x8*)(kb + 32 * KP + ks * 32);
;             if (ks == 0) { p0 = __builtin_amdgcn_mfma_f32_32x32x16_bf16(k0, qf[0], negm, 0, 0, 0); p1 = __builtin_amdgcn_mfma_f32_32x32x16_bf16(k1, qf[0], negm, 0, 0, 0); }
;             else { p0 = __builtin_amdgcn_mfma_f32_32x32x16_bf16(k0, qf[ks], p0, 0, 0, 0); p1 = __builtin_amdgcn_mfma_f32_32x32x16_bf16(k1, qf[ks], p1, 0, 0, 0); }
;         }
;         if (BIAS) {
;             asm volatile("s_nop 15\n\ts_nop 7" : "+v"(p0), "+v"(p1));
;             const float d0 = qp - (float)(t * 64 + 4 * hi);
; #pragma unroll
;             for (int r = 0; r < 16; ++r) { const float dk = d0 - (float)((r & 3) + 8 * (r >> 2)); p0[r] = p0[r] - sl2 * fabsf(dk); p1[r] = p1[r] - sl2 * fabsf(dk - 32.f); }
;         } else {
;             asm volatile("s_nop 15\n\ts_nop 7" : "+v"(p0), "+v"(p1));
;         }
;     ...
;             const LAS unsigned char* vbase = lds + VOFF + vcur * VBUF + (4 * hi + ((lane & 15) >> 2)) * 64 + ((lane >> 4) & 1) * 32 + (lane & 3) * 8;
;             float ls = 0.f;
; #pragma unroll
;             for (int hs = 0; hs < 4; ++hs) {
;                 float e[8];
; #pragma unroll
;                 for (int j = 0; j < 8; ++j) { e[j] = __builtin_amdgcn_exp2f(hs < 2 ? p0[8 * (hs & 1) + j] : p1[8 * (hs & 1) + j]); ls += e[j]; }
;                 pw[hs].x = cvtpk(e[0], e[1]); pw[hs].y = cvtpk(e[2], e[3]); pw[hs].z = cvtpk(e[4], e[5]); pw[hs].w = cvtpk(e[6], e[7]);
;                 const bf16x8 pbv = __builtin_bit_cast(bf16x8, pw[hs]);
; #pragma unroll
;                 for (int d = 0; d < NDT; ++d) { const LAS unsigned char* vp = vbase + d * 4096 + hs * 1024;
;                     const v4i16_t a0 = __builtin_amdgcn_ds_read_tr16_b64_v4i16((LAS v4i16_t*)vp), a1 = __builtin_amdgcn_ds_read_tr16_b64_v4i16((LAS v4i16_t*)(vp + 512));
;                     const bf16x8 av = {a0[0], a0[1], a0[2], a0[3], a1[0], a1[1], a1[2], a1[3]};
;                     o[d] = __builtin_amdgcn_mfma_f32_32x32x16_bf16(av, pbv, o[d], 0, 0, 0); }
;                 __builtin_amdgcn_sched_barrier(0);
;             }
;             l += ls;
.LBB0_645:
	v_exp_f32_e32 v165, v82
	v_exp_f32_e32 v166, v83
	v_exp_f32_e32 v167, v84
	v_exp_f32_e32 v169, v85
	v_exp_f32_e32 v174, v86
	v_exp_f32_e32 v175, v87
	ds_read_b64_tr_b16 v[82:83], v161 offset:53248
	ds_read_b64_tr_b16 v[84:85], v161 offset:53760
	v_exp_f32_e32 v176, v88
	v_exp_f32_e32 v177, v89
	ds_read_b64_tr_b16 v[170:171], v161 offset:57344
	ds_read_b64_tr_b16 v[172:173], v161 offset:57856
	v_cvt_pk_bf16_f32 v86, v165, v166
	v_cvt_pk_bf16_f32 v87, v167, v169
	v_cvt_pk_bf16_f32 v88, v174, v175
	v_cvt_pk_bf16_f32 v89, v176, v177
	s_waitcnt lgkmcnt(2)
	s_nop 0
	v_mfma_f32_32x32x16_bf16 v[18:33], v[82:85], v[86:89], v[18:33]
	v_add_f32_e32 v82, 0, v165
	v_add_f32_e32 v82, v166, v82
	v_add_f32_e32 v82, v167, v82
	v_add_f32_e32 v82, v169, v82
	v_add_f32_e32 v82, v174, v82
	v_add_f32_e32 v82, v175, v82
	v_add_f32_e32 v82, v176, v82
	s_waitcnt lgkmcnt(0)
	v_mfma_f32_32x32x16_bf16 v[2:17], v[170:173], v[86:89], v[2:17]
	v_add_f32_e32 v165, v177, v82
	v_exp_f32_e32 v166, v90
	v_exp_f32_e32 v167, v91
	v_exp_f32_e32 v169, v92
	v_exp_f32_e32 v170, v93
	v_exp_f32_e32 v94, v94
	v_exp_f32_e32 v95, v95
	ds_read_b64_tr_b16 v[82:83], v161 offset:54272
	ds_read_b64_tr_b16 v[84:85], v161 offset:54784
	v_exp_f32_e32 v96, v96
	v_exp_f32_e32 v97, v97
	ds_read_b64_tr_b16 v[90:91], v161 offset:58368
	ds_read_b64_tr_b16 v[92:93], v161 offset:58880
	v_cvt_pk_bf16_f32 v86, v166, v167
	v_cvt_pk_bf16_f32 v87, v169, v170
	v_cvt_pk_bf16_f32 v88, v94, v95
	v_cvt_pk_bf16_f32 v89, v96, v97
	s_waitcnt lgkmcnt(2)
	s_nop 0
	v_mfma_f32_32x32x16_bf16 v[18:33], v[82:85], v[86:89], v[18:33]
	v_add_f32_e32 v82, v166, v165
	v_add_f32_e32 v82, v167, v82
	v_add_f32_e32 v82, v169, v82
	v_add_f32_e32 v82, v170, v82
	v_add_f32_e32 v82, v94, v82
	v_add_f32_e32 v82, v95, v82
	v_add_f32_e32 v82, v96, v82
	s_waitcnt lgkmcnt(0)
	v_mfma_f32_32x32x16_bf16 v[2:17], v[90:93], v[86:89], v[2:17]
	v_add_f32_e32 v86, v97, v82
	v_exp_f32_e32 v87, v66
	v_exp_f32_e32 v88, v67
	v_exp_f32_e32 v89, v68
	v_exp_f32_e32 v90, v69
	v_exp_f32_e32 v91, v70
	v_exp_f32_e32 v92, v71
	ds_read_b64_tr_b16 v[66:67], v161 offset:55296
	ds_read_b64_tr_b16 v[68:69], v161 offset:55808
	v_exp_f32_e32 v93, v72
	v_exp_f32_e32 v94, v73
	ds_read_b64_tr_b16 v[82:83], v161 offset:59392
	ds_read_b64_tr_b16 v[84:85], v161 offset:59904
	v_cvt_pk_bf16_f32 v70, v87, v88
	v_cvt_pk_bf16_f32 v71, v89, v90
	v_cvt_pk_bf16_f32 v72, v91, v92
	v_cvt_pk_bf16_f32 v73, v93, v94
	s_waitcnt lgkmcnt(2)
	s_nop 0
	v_mfma_f32_32x32x16_bf16 v[18:33], v[66:69], v[70:73], v[18:33]
	v_add_f32_e32 v66, v87, v86
	v_add_f32_e32 v66, v88, v66
	v_add_f32_e32 v66, v89, v66
	v_add_f32_e32 v66, v90, v66
	v_add_f32_e32 v66, v91, v66
	v_add_f32_e32 v66, v92, v66
	v_add_f32_e32 v66, v93, v66
	s_waitcnt lgkmcnt(0)
	v_mfma_f32_32x32x16_bf16 v[2:17], v[82:85], v[70:73], v[2:17]
	v_add_f32_e32 v82, v94, v66
	v_exp_f32_e32 v83, v74
	v_exp_f32_e32 v84, v75
	v_exp_f32_e32 v85, v76
	v_exp_f32_e32 v86, v77
	v_exp_f32_e32 v78, v78
	v_exp_f32_e32 v79, v79
	ds_read_b64_tr_b16 v[66:67], v161 offset:56320
	ds_read_b64_tr_b16 v[68:69], v161 offset:56832
	v_exp_f32_e32 v80, v80
	v_exp_f32_e32 v81, v81
	ds_read_b64_tr_b16 v[74:75], v161 offset:60416
	ds_read_b64_tr_b16 v[76:77], v161 offset:60928
	v_cvt_pk_bf16_f32 v70, v83, v84
	v_cvt_pk_bf16_f32 v71, v85, v86
	v_cvt_pk_bf16_f32 v72, v78, v79
	v_cvt_pk_bf16_f32 v73, v80, v81
	s_waitcnt lgkmcnt(2)
	s_nop 0
	v_mfma_f32_32x32x16_bf16 v[18:33], v[66:69], v[70:73], v[18:33]
	v_add_f32_e32 v66, v83, v82
	v_add_f32_e32 v66, v84, v66
	v_add_f32_e32 v66, v85, v66
	v_add_f32_e32 v66, v86, v66
	v_add_f32_e32 v66, v78, v66
	v_add_f32_e32 v66, v79, v66
	v_add_f32_e32 v66, v80, v66
	s_waitcnt lgkmcnt(0)
	v_mfma_f32_32x32x16_bf16 v[2:17], v[74:77], v[70:73], v[2:17]
	v_add_f32_e32 v165, v81, v66
	ds_read_b128 v[66:69], v148 offset:13312
	ds_read_b128 v[170:173], v148 offset:13344
	ds_read_b128 v[174:177], v148 offset:19968
	ds_read_b128 v[178:181], v148 offset:20000
	v_add_f32_e32 v164, v164, v165
	s_waitcnt lgkmcnt(3)
	v_mfma_f32_32x32x16_bf16 v[82:97], v[66:69], v[98:101], v[34:49]
	s_waitcnt lgkmcnt(1)
	v_mfma_f32_32x32x16_bf16 v[66:81], v[174:177], v[98:101], v[34:49]
	v_mfma_f32_32x32x16_bf16 v[82:97], v[170:173], v[102:105], v[82:97]
	ds_read_b128 v[170:173], v148 offset:13376
	ds_read_b128 v[174:177], v148 offset:13408
	s_waitcnt lgkmcnt(2)
	v_mfma_f32_32x32x16_bf16 v[66:81], v[178:181], v[102:105], v[66:81]
	s_waitcnt lgkmcnt(1)
	v_mfma_f32_32x32x16_bf16 v[82:97], v[170:173], v[106:109], v[82:97]
	ds_read_b128 v[170:173], v148 offset:20032
	ds_read_b128 v[178:181], v148 offset:20064
	s_waitcnt lgkmcnt(1)
	v_mfma_f32_32x32x16_bf16 v[66:81], v[170:173], v[106:109], v[66:81]
	v_mfma_f32_32x32x16_bf16 v[82:97], v[174:177], v[110:113], v[82:97]
	ds_read_b128 v[170:173], v148 offset:13440
	ds_read_b128 v[174:177], v148 offset:13472
	s_waitcnt lgkmcnt(2)
	v_mfma_f32_32x32x16_bf16 v[66:81], v[178:181], v[110:113], v[66:81]
	s_waitcnt lgkmcnt(1)
	v_mfma_f32_32x32x16_bf16 v[82:97], v[170:173], v[114:117], v[82:97]
	ds_read_b128 v[170:173], v148 offset:20096
	ds_read_b128 v[178:181], v148 offset:20128
	s_waitcnt lgkmcnt(1)
	v_mfma_f32_32x32x16_bf16 v[66:81], v[170:173], v[114:117], v[66:81]
	v_mfma_f32_32x32x16_bf16 v[82:97], v[174:177], v[118:121], v[82:97]
	s_waitcnt lgkmcnt(0)
	v_mfma_f32_32x32x16_bf16 v[66:81], v[178:181], v[118:121], v[66:81]
	s_nop 15
	s_nop 7
	s_nop 0
	v_max3_f32 v165, v82, v83, v66
	v_max3_f32 v166, v84, v85, v67
	v_max3_f32 v165, v165, v68, v69
	v_max3_f32 v166, v166, v88, v89
	v_max3_f32 v165, v165, v86, v87
	v_max3_f32 v166, v166, v72, v73
	v_max3_f32 v165, v165, v70, v71
	v_max3_f32 v166, v166, v92, v93
	v_max3_f32 v165, v165, v90, v91
	v_max3_f32 v166, v166, v76, v77
	v_max3_f32 v165, v165, v74, v75
	v_max3_f32 v166, v166, v96, v97
	v_max3_f32 v165, v165, v94, v95
	v_max3_f32 v166, v166, v80, v81
	v_max3_f32 v165, v165, v78, v79
	v_max_f32_e32 v165, v165, v166
	v_cmp_lt_f32_e32 vcc, s59, v165
	s_cbranch_vccz .LBB0_647
; template <int DQK, int DV, bool BIAS> ...
;     ...
;         if (__any(mx > 8.f)) {
;             mx = fmaxf(mx, __shfl_xor(mx, 32));
;             const float dl = fmaxf(mx, 0.f); mhat += dl;
;             const float f = __builtin_amdgcn_exp2f(-dl);
; #pragma unroll
;             for (int r = 0; r < 16; ++r) { p0[r] -= dl; p1[r] -= dl; negm[r] = -mhat; }
;             l *= f;
; #pragma unroll
;             for (int d = 0; d < NDT; ++d)
; #pragma unroll
;                 for (int r = 0; r < 16; ++r) o[d][r] *= f;
;         }
	ds_bpermute_b32 v34, v168, v165
	s_waitcnt lgkmcnt(0)
	v_max3_f32 v36, v165, v34, 0
	v_exp_f32_e64 v38, -v36
	v_add_f32_e32 v153, v153, v36
	v_xor_b32_e32 v34, 0x80000000, v153
	v_pk_add_f32 v[82:83], v[82:83], v[36:37] op_sel_hi:[1,0] neg_lo:[0,1] neg_hi:[0,1]
	v_pk_add_f32 v[66:67], v[66:67], v[36:37] op_sel_hi:[1,0] neg_lo:[0,1] neg_hi:[0,1]
	v_pk_add_f32 v[84:85], v[84:85], v[36:37] op_sel_hi:[1,0] neg_lo:[0,1] neg_hi:[0,1]
	v_pk_add_f32 v[68:69], v[68:69], v[36:37] op_sel_hi:[1,0] neg_lo:[0,1] neg_hi:[0,1]
	v_pk_add_f32 v[86:87], v[86:87], v[36:37] op_sel_hi:[1,0] neg_lo:[0,1] neg_hi:[0,1]
	v_pk_add_f32 v[70:71], v[70:71], v[36:37] op_sel_hi:[1,0] neg_lo:[0,1] neg_hi:[0,1]
	v_pk_add_f32 v[88:89], v[88:89], v[36:37] op_sel_hi:[1,0] neg_lo:[0,1] neg_hi:[0,1]
	v_pk_add_f32 v[72:73], v[72:73], v[36:37] op_sel_hi:[1,0] neg_lo:[0,1] neg_hi:[0,1]
	v_pk_add_f32 v[90:91], v[90:91], v[36:37] op_sel_hi:[1,0] neg_lo:[0,1] neg_hi:[0,1]
	v_pk_add_f32 v[74:75], v[74:75], v[36:37] op_sel_hi:[1,0] neg_lo:[0,1] neg_hi:[0,1]
	v_pk_add_f32 v[92:93], v[92:93], v[36:37] op_sel_hi:[1,0] neg_lo:[0,1] neg_hi:[0,1]
	v_pk_add_f32 v[76:77], v[76:77], v[36:37] op_sel_hi:[1,0] neg_lo:[0,1] neg_hi:[0,1]
	v_pk_add_f32 v[94:95], v[94:95], v[36:37] op_sel_hi:[1,0] neg_lo:[0,1] neg_hi:[0,1]
	v_pk_add_f32 v[78:79], v[78:79], v[36:37] op_sel_hi:[1,0] neg_lo:[0,1] neg_hi:[0,1]
	v_pk_add_f32 v[96:97], v[96:97], v[36:37] op_sel_hi:[1,0] neg_lo:[0,1] neg_hi:[0,1]
	v_pk_add_f32 v[80:81], v[80:81], v[36:37] op_sel_hi:[1,0] neg_lo:[0,1] neg_hi:[0,1]
	v_pk_mul_f32 v[32:33], v[32:33], v[38:39] op_sel_hi:[1,0]
	v_pk_mul_f32 v[30:31], v[30:31], v[38:39] op_sel_hi:[1,0]
	v_pk_mul_f32 v[28:29], v[28:29], v[38:39] op_sel_hi:[1,0]
	v_pk_mul_f32 v[26:27], v[26:27], v[38:39] op_sel_hi:[1,0]
	v_pk_mul_f32 v[24:25], v[24:25], v[38:39] op_sel_hi:[1,0]
	v_pk_mul_f32 v[22:23], v[22:23], v[38:39] op_sel_hi:[1,0]
	v_pk_mul_f32 v[20:21], v[20:21], v[38:39] op_sel_hi:[1,0]
	v_pk_mul_f32 v[18:19], v[18:19], v[38:39] op_sel_hi:[1,0]
	v_pk_mul_f32 v[16:17], v[16:17], v[38:39] op_sel_hi:[1,0]
	v_pk_mul_f32 v[14:15], v[14:15], v[38:39] op_sel_hi:[1,0]
	v_pk_mul_f32 v[12:13], v[12:13], v[38:39] op_sel_hi:[1,0]
	v_pk_mul_f32 v[10:11], v[10:11], v[38:39] op_sel_hi:[1,0]
	v_pk_mul_f32 v[8:9], v[8:9], v[38:39] op_sel_hi:[1,0]
	v_pk_mul_f32 v[6:7], v[6:7], v[38:39] op_sel_hi:[1,0]
	v_pk_mul_f32 v[4:5], v[4:5], v[38:39] op_sel_hi:[1,0]
	v_pk_mul_f32 v[2:3], v[2:3], v[38:39] op_sel_hi:[1,0]
	v_mul_f32_e32 v164, v164, v38
	v_mov_b32_e32 v35, v34
	v_mov_b32_e32 v36, v34
	v_mov_b32_e32 v37, v34
	v_mov_b32_e32 v38, v34
	v_mov_b32_e32 v39, v34
	v_mov_b32_e32 v40, v34
	v_mov_b32_e32 v41, v34
	v_mov_b32_e32 v42, v34
	v_mov_b32_e32 v43, v34
	v_mov_b32_e32 v44, v34
	v_mov_b32_e32 v45, v34
	v_mov_b32_e32 v46, v34
	v_mov_b32_e32 v47, v34
	v_mov_b32_e32 v48, v34
	v_mov_b32_e32 v49, v34
	v_mov_b32_e32 v50, v34
	v_mov_b32_e32 v51, v34
	v_mov_b32_e32 v52, v34
	v_mov_b32_e32 v53, v34
	v_mov_b32_e32 v54, v34
	v_mov_b32_e32 v55, v34
	v_mov_b32_e32 v56, v34
	v_mov_b32_e32 v57, v34
	v_mov_b32_e32 v58, v34
	v_mov_b32_e32 v59, v34
	v_mov_b32_e32 v60, v34
	v_mov_b32_e32 v61, v34
	v_mov_b32_e32 v62, v34
	v_mov_b32_e32 v63, v34
	v_mov_b32_e32 v64, v34
	v_mov_b32_e32 v65, v34

; #define LAS __attribute__((address_space(3)))
; __device__ __forceinline__ float max3f(float a, float b, float c) { float r; asm("v_max3_f32 %0, %1, %2, %3" : "=v"(r) : "v"(a), "v"(b), "v"(c)); return r; }
; template <int DQK, int DV, bool BIAS> ...
;     ...
;         const LAS unsigned char* kb = lds + buf * KBUF + r32 * KP + hi * 16;
; #pragma unroll
;         for (int ks = 0; ks < NKS; ++ks) {
;             const bf16x8 k0 = *(const LAS bf16x8*)(kb + ks * 32), k1 = *(const LAS bf16x8*)(kb + 32 * KP + ks * 32);
;             if (ks == 0) { p0 = __builtin_amdgcn_mfma_f32_32x32x16_bf16(k0, qf[0], negm, 0, 0, 0); p1 = __builtin_amdgcn_mfma_f32_32x32x16_bf16(k1, qf[0], negm, 0, 0, 0); }
;             else { p0 = __builtin_amdgcn_mfma_f32_32x32x16_bf16(k0, qf[ks], p0, 0, 0, 0); p1 = __builtin_amdgcn_mfma_f32_32x32x16_bf16(k1, qf[ks], p1, 0, 0, 0); }
;         }
;         if (BIAS) {
;             asm volatile("s_nop 15\n\ts_nop 7" : "+v"(p0), "+v"(p1));
;             const float d0 = qp - (float)(t * 64 + 4 * hi);
; #pragma unroll
;             for (int r = 0; r < 16; ++r) { const float dk = d0 - (float)((r & 3) + 8 * (r >> 2)); p0[r] = p0[r] - sl2 * fabsf(dk); p1[r] = p1[r] - sl2 * fabsf(dk - 32.f); }
;         } else {
;             asm volatile("s_nop 15\n\ts_nop 7" : "+v"(p0), "+v"(p1));
;         }
;         float mxa = max3f(p0[0], p0[1], p1[0]), mxb = max3f(p0[2], p0[3], p1[1]); mxa = max3f(mxa, p1[2], p1[3]);
; #pragma unroll
;         for (int r = 4; r < 16; r += 4) { mxa = max3f(mxa, p0[r], p0[r + 1]); mxb = max3f(mxb, p0[r + 2], p0[r + 3]); mxa = max3f(mxa, p1[r], p1[r + 1]); mxb = max3f(mxb, p1[r + 2], p1[r + 3]); }
;         float mx = fmaxf(mxa, mxb);
;         if (__any(mx > 8.f)) {
;             mx = fmaxf(mx, __shfl_xor(mx, 32));
;             const float dl = fmaxf(mx, 0.f); mhat += dl;
;             const float f = __builtin_amdgcn_exp2f(-dl);
; #pragma unroll
;             for (int r = 0; r < 16; ++r) { p0[r] -= dl; p1[r] -= dl; negm[r] = -mhat; }
;             l *= f;
; #pragma unroll
;             for (int d = 0; d < NDT; ++d)
; #pragma unroll
;                 for (int r = 0; r < 16; ++r) o[d][r] *= f;
;         }
.LBB0_658:
	ds_read_b128 v[66:69], v148 offset:26624
	ds_read_b128 v[198:201], v148 offset:26656
	ds_read_b128 v[202:205], v148 offset:33280
	ds_read_b128 v[206:209], v148 offset:33312
	v_add_f32_e32 v170, 0, v170
	v_add_f32_e32 v170, v171, v170
	s_waitcnt lgkmcnt(3)
	v_mfma_f32_32x32x16_bf16 v[82:97], v[66:69], v[98:101], v[34:49]
	v_add_f32_e32 v165, v165, v170
	v_add_f32_e32 v165, v166, v165
	v_add_f32_e32 v165, v167, v165
	v_add_f32_e32 v165, v169, v165
	v_add_f32_e32 v165, v172, v165
	v_add_f32_e32 v165, v173, v165
	v_add_f32_e32 v165, v175, v165
	s_waitcnt lgkmcnt(1)
	v_mfma_f32_32x32x16_bf16 v[66:81], v[202:205], v[98:101], v[34:49]
	v_add_f32_e32 v165, v176, v165
	v_add_f32_e32 v165, v177, v165
	v_add_f32_e32 v165, v178, v165
	v_add_f32_e32 v165, v179, v165
	v_add_f32_e32 v165, v174, v165
	v_add_f32_e32 v165, v180, v165
	v_add_f32_e32 v165, v181, v165
	v_mfma_f32_32x32x16_bf16 v[82:97], v[198:201], v[102:105], v[82:97]
	ds_read_b128 v[198:201], v148 offset:26688
	ds_read_b128 v[202:205], v148 offset:26720
	v_add_f32_e32 v165, v185, v165
	v_add_f32_e32 v165, v186, v165
	v_add_f32_e32 v165, v187, v165
	v_add_f32_e32 v165, v182, v165
	v_add_f32_e32 v165, v183, v165
	v_add_f32_e32 v165, v184, v165
	s_waitcnt lgkmcnt(2)
	v_mfma_f32_32x32x16_bf16 v[66:81], v[206:209], v[102:105], v[66:81]
	v_add_f32_e32 v165, v188, v165
	v_add_f32_e32 v165, v189, v165
	v_add_f32_e32 v165, v194, v165
	v_add_f32_e32 v165, v195, v165
	v_add_f32_e32 v165, v190, v165
	v_add_f32_e32 v165, v191, v165
	v_add_f32_e32 v165, v192, v165
	s_waitcnt lgkmcnt(1)
	v_mfma_f32_32x32x16_bf16 v[82:97], v[198:201], v[106:109], v[82:97]
	ds_read_b128 v[198:201], v148 offset:33344
	ds_read_b128 v[206:209], v148 offset:33376
	ds_read_b128 v[170:173], v148 offset:26752
	v_add_f32_e32 v165, v193, v165
	v_add_f32_e32 v165, v196, v165
	v_add_f32_e32 v165, v197, v165
	v_add_f32_e32 v164, v164, v165
	s_waitcnt lgkmcnt(2)
	v_mfma_f32_32x32x16_bf16 v[66:81], v[198:201], v[106:109], v[66:81]
	ds_read_b128 v[176:179], v148 offset:33408
	ds_read_b128 v[198:201], v148 offset:26784
	v_mfma_f32_32x32x16_bf16 v[82:97], v[202:205], v[110:113], v[82:97]
	s_waitcnt lgkmcnt(3)
	v_mfma_f32_32x32x16_bf16 v[66:81], v[206:209], v[110:113], v[66:81]
	s_waitcnt lgkmcnt(2)
	v_mfma_f32_32x32x16_bf16 v[82:97], v[170:173], v[114:117], v[82:97]
	ds_read_b128 v[170:173], v148 offset:33440
	s_waitcnt lgkmcnt(2)
	v_mfma_f32_32x32x16_bf16 v[66:81], v[176:179], v[114:117], v[66:81]
	s_waitcnt lgkmcnt(1)
	v_mfma_f32_32x32x16_bf16 v[82:97], v[198:201], v[118:121], v[82:97]
	s_waitcnt lgkmcnt(0)
	v_mfma_f32_32x32x16_bf16 v[66:81], v[170:173], v[118:121], v[66:81]
	s_nop 15
	s_nop 7
	s_nop 0
	v_max3_f32 v165, v82, v83, v66
	v_max3_f32 v166, v84, v85, v67
	v_max3_f32 v165, v165, v68, v69
	v_max3_f32 v166, v166, v88, v89
	v_max3_f32 v165, v165, v86, v87
	v_max3_f32 v166, v166, v72, v73
	v_max3_f32 v165, v165, v70, v71
	v_max3_f32 v166, v166, v92, v93
	v_max3_f32 v165, v165, v90, v91
	v_max3_f32 v166, v166, v76, v77
	v_max3_f32 v165, v165, v74, v75
	v_max3_f32 v166, v166, v96, v97
	v_max3_f32 v165, v165, v94, v95
	v_max3_f32 v166, v166, v80, v81
	v_max3_f32 v165, v165, v78, v79
	v_max_f32_e32 v165, v165, v166
	v_cmp_lt_f32_e32 vcc, s59, v165
	s_cbranch_vccz .LBB0_660
	ds_bpermute_b32 v34, v168, v165
	s_waitcnt lgkmcnt(0)
	v_max3_f32 v36, v165, v34, 0
	v_exp_f32_e64 v38, -v36
	v_add_f32_e32 v153, v153, v36
	v_xor_b32_e32 v34, 0x80000000, v153
	v_pk_add_f32 v[82:83], v[82:83], v[36:37] op_sel_hi:[1,0] neg_lo:[0,1] neg_hi:[0,1]
	v_pk_add_f32 v[66:67], v[66:67], v[36:37] op_sel_hi:[1,0] neg_lo:[0,1] neg_hi:[0,1]
	v_pk_add_f32 v[84:85], v[84:85], v[36:37] op_sel_hi:[1,0] neg_lo:[0,1] neg_hi:[0,1]
	v_pk_add_f32 v[68:69], v[68:69], v[36:37] op_sel_hi:[1,0] neg_lo:[0,1] neg_hi:[0,1]
	v_pk_add_f32 v[86:87], v[86:87], v[36:37] op_sel_hi:[1,0] neg_lo:[0,1] neg_hi:[0,1]
	v_pk_add_f32 v[70:71], v[70:71], v[36:37] op_sel_hi:[1,0] neg_lo:[0,1] neg_hi:[0,1]
	v_pk_add_f32 v[88:89], v[88:89], v[36:37] op_sel_hi:[1,0] neg_lo:[0,1] neg_hi:[0,1]
	v_pk_add_f32 v[72:73], v[72:73], v[36:37] op_sel_hi:[1,0] neg_lo:[0,1] neg_hi:[0,1]
	v_pk_add_f32 v[90:91], v[90:91], v[36:37] op_sel_hi:[1,0] neg_lo:[0,1] neg_hi:[0,1]
	v_pk_add_f32 v[74:75], v[74:75], v[36:37] op_sel_hi:[1,0] neg_lo:[0,1] neg_hi:[0,1]
	v_pk_add_f32 v[92:93], v[92:93], v[36:37] op_sel_hi:[1,0] neg_lo:[0,1] neg_hi:[0,1]
	v_pk_add_f32 v[76:77], v[76:77], v[36:37] op_sel_hi:[1,0] neg_lo:[0,1] neg_hi:[0,1]
	v_pk_add_f32 v[94:95], v[94:95], v[36:37] op_sel_hi:[1,0] neg_lo:[0,1] neg_hi:[0,1]
	v_pk_add_f32 v[78:79], v[78:79], v[36:37] op_sel_hi:[1,0] neg_lo:[0,1] neg_hi:[0,1]
	v_pk_add_f32 v[96:97], v[96:97], v[36:37] op_sel_hi:[1,0] neg_lo:[0,1] neg_hi:[0,1]
	v_pk_add_f32 v[80:81], v[80:81], v[36:37] op_sel_hi:[1,0] neg_lo:[0,1] neg_hi:[0,1]
	v_pk_mul_f32 v[32:33], v[32:33], v[38:39] op_sel_hi:[1,0]
	v_pk_mul_f32 v[30:31], v[30:31], v[38:39] op_sel_hi:[1,0]
	v_pk_mul_f32 v[28:29], v[28:29], v[38:39] op_sel_hi:[1,0]
	v_pk_mul_f32 v[26:27], v[26:27], v[38:39] op_sel_hi:[1,0]
	v_pk_mul_f32 v[24:25], v[24:25], v[38:39] op_sel_hi:[1,0]
	v_pk_mul_f32 v[22:23], v[22:23], v[38:39] op_sel_hi:[1,0]
	v_pk_mul_f32 v[20:21], v[20:21], v[38:39] op_sel_hi:[1,0]
	v_pk_mul_f32 v[18:19], v[18:19], v[38:39] op_sel_hi:[1,0]
	v_pk_mul_f32 v[16:17], v[16:17], v[38:39] op_sel_hi:[1,0]
	v_pk_mul_f32 v[14:15], v[14:15], v[38:39] op_sel_hi:[1,0]
	v_pk_mul_f32 v[12:13], v[12:13], v[38:39] op_sel_hi:[1,0]
	v_pk_mul_f32 v[10:11], v[10:11], v[38:39] op_sel_hi:[1,0]
	v_pk_mul_f32 v[8:9], v[8:9], v[38:39] op_sel_hi:[1,0]
	v_pk_mul_f32 v[6:7], v[6:7], v[38:39] op_sel_hi:[1,0]
	v_pk_mul_f32 v[4:5], v[4:5], v[38:39] op_sel_hi:[1,0]
	v_pk_mul_f32 v[2:3], v[2:3], v[38:39] op_sel_hi:[1,0]
	v_mul_f32_e32 v164, v164, v38
	v_mov_b32_e32 v35, v34
	v_mov_b32_e32 v36, v34
	v_mov_b32_e32 v37, v34
	v_mov_b32_e32 v38, v34
	v_mov_b32_e32 v39, v34
	v_mov_b32_e32 v40, v34
	v_mov_b32_e32 v41, v34
	v_mov_b32_e32 v42, v34
	v_mov_b32_e32 v43, v34
	v_mov_b32_e32 v44, v34
	v_mov_b32_e32 v45, v34
	v_mov_b32_e32 v46, v34
	v_mov_b32_e32 v47, v34
	v_mov_b32_e32 v48, v34
	v_mov_b32_e32 v49, v34
	v_mov_b32_e32 v50, v34
	v_mov_b32_e32 v51, v34
	v_mov_b32_e32 v52, v34
	v_mov_b32_e32 v53, v34
	v_mov_b32_e32 v54, v34
	v_mov_b32_e32 v55, v34
	v_mov_b32_e32 v56, v34
	v_mov_b32_e32 v57, v34
	v_mov_b32_e32 v58, v34
	v_mov_b32_e32 v59, v34
	v_mov_b32_e32 v60, v34
	v_mov_b32_e32 v61, v34
	v_mov_b32_e32 v62, v34
	v_mov_b32_e32 v63, v34
	v_mov_b32_e32 v64, v34
	v_mov_b32_e32 v65, v34
; #define LAS __attribute__((address_space(3)))
; template <int DQK, int DV, bool BIAS> ...
;     ...
;         const LAS unsigned char* kb = lds + buf * KBUF + r32 * KP + hi * 16;
; #pragma unroll
;         for (int ks = 0; ks < NKS; ++ks) {
;             const bf16x8 k0 = *(const LAS bf16x8*)(kb + ks * 32), k1 = *(const LAS bf16x8*)(kb + 32 * KP + ks * 32);
;             if (ks == 0) { p0 = __builtin_amdgcn_mfma_f32_32x32x16_bf16(k0, qf[0], negm, 0, 0, 0); p1 = __builtin_amdgcn_mfma_f32_32x32x16_bf16(k1, qf[0], negm, 0, 0, 0); }
;             else { p0 = __builtin_amdgcn_mfma_f32_32x32x16_bf16(k0, qf[ks], p0, 0, 0, 0); p1 = __builtin_amdgcn_mfma_f32_32x32x16_bf16(k1, qf[ks], p1, 0, 0, 0); }
;         }
;         if (BIAS) {
;             asm volatile("s_nop 15\n\ts_nop 7" : "+v"(p0), "+v"(p1));
;             const float d0 = qp - (float)(t * 64 + 4 * hi);
; #pragma unroll
;             for (int r = 0; r < 16; ++r) { const float dk = d0 - (float)((r & 3) + 8 * (r >> 2)); p0[r] = p0[r] - sl2 * fabsf(dk); p1[r] = p1[r] - sl2 * fabsf(dk - 32.f); }
;         } else {
;             asm volatile("s_nop 15\n\ts_nop 7" : "+v"(p0), "+v"(p1));
;         }
;     ...
;             const LAS unsigned char* vbase = lds + VOFF + vcur * VBUF + (4 * hi + ((lane & 15) >> 2)) * 64 + ((lane >> 4) & 1) * 32 + (lane & 3) * 8;
;             float ls = 0.f;
; #pragma unroll
;             for (int hs = 0; hs < 4; ++hs) {
;                 float e[8];
; #pragma unroll
;                 for (int j = 0; j < 8; ++j) { e[j] = __builtin_amdgcn_exp2f(hs < 2 ? p0[8 * (hs & 1) + j] : p1[8 * (hs & 1) + j]); ls += e[j]; }
;                 pw[hs].x = cvtpk(e[0], e[1]); pw[hs].y = cvtpk(e[2], e[3]); pw[hs].z = cvtpk(e[4], e[5]); pw[hs].w = cvtpk(e[6], e[7]);
;                 const bf16x8 pbv = __builtin_bit_cast(bf16x8, pw[hs]);
; #pragma unroll
;                 for (int d = 0; d < NDT; ++d) { const LAS unsigned char* vp = vbase + d * 4096 + hs * 1024;
;                     const v4i16_t a0 = __builtin_amdgcn_ds_read_tr16_b64_v4i16((LAS v4i16_t*)vp), a1 = __builtin_amdgcn_ds_read_tr16_b64_v4i16((LAS v4i16_t*)(vp + 512));
;                     const bf16x8 av = {a0[0], a0[1], a0[2], a0[3], a1[0], a1[1], a1[2], a1[3]};
;                     o[d] = __builtin_amdgcn_mfma_f32_32x32x16_bf16(av, pbv, o[d], 0, 0, 0); }
;                 __builtin_amdgcn_sched_barrier(0);
;             }
;             l += ls;
.LBB0_660:
	v_exp_f32_e32 v165, v82
	v_exp_f32_e32 v166, v83
	v_exp_f32_e32 v167, v84
	v_exp_f32_e32 v169, v85
	v_exp_f32_e32 v174, v86
	v_exp_f32_e32 v175, v87
	ds_read_b64_tr_b16 v[82:83], v162 offset:16384
	ds_read_b64_tr_b16 v[84:85], v162 offset:16896
	v_exp_f32_e32 v176, v88
	v_exp_f32_e32 v177, v89
	ds_read_b64_tr_b16 v[170:171], v162 offset:20480
	ds_read_b64_tr_b16 v[172:173], v162 offset:20992
	v_cvt_pk_bf16_f32 v86, v165, v166
	v_cvt_pk_bf16_f32 v87, v167, v169
	v_cvt_pk_bf16_f32 v88, v174, v175
	v_cvt_pk_bf16_f32 v89, v176, v177
	s_waitcnt lgkmcnt(2)
	s_nop 0
	v_mfma_f32_32x32x16_bf16 v[18:33], v[82:85], v[86:89], v[18:33]
	v_add_f32_e32 v82, 0, v165
	v_add_f32_e32 v82, v166, v82
	v_add_f32_e32 v82, v167, v82
	v_add_f32_e32 v82, v169, v82
	v_add_f32_e32 v82, v174, v82
	v_add_f32_e32 v82, v175, v82
	v_add_f32_e32 v82, v176, v82
	s_waitcnt lgkmcnt(0)
	v_mfma_f32_32x32x16_bf16 v[2:17], v[170:173], v[86:89], v[2:17]
	v_add_f32_e32 v165, v177, v82
	v_exp_f32_e32 v166, v90
	v_exp_f32_e32 v167, v91
	v_exp_f32_e32 v169, v92
	v_exp_f32_e32 v170, v93
	v_exp_f32_e32 v94, v94
	v_exp_f32_e32 v95, v95
	ds_read_b64_tr_b16 v[82:83], v162 offset:17408
	ds_read_b64_tr_b16 v[84:85], v162 offset:17920
	v_exp_f32_e32 v96, v96
	v_exp_f32_e32 v97, v97
	ds_read_b64_tr_b16 v[90:91], v162 offset:21504
	ds_read_b64_tr_b16 v[92:93], v162 offset:22016
	v_cvt_pk_bf16_f32 v86, v166, v167
	v_cvt_pk_bf16_f32 v87, v169, v170
	v_cvt_pk_bf16_f32 v88, v94, v95
	v_cvt_pk_bf16_f32 v89, v96, v97
	s_waitcnt lgkmcnt(2)
	s_nop 0
	v_mfma_f32_32x32x16_bf16 v[18:33], v[82:85], v[86:89], v[18:33]
	v_add_f32_e32 v82, v166, v165
	v_add_f32_e32 v82, v167, v82
	v_add_f32_e32 v82, v169, v82
	v_add_f32_e32 v82, v170, v82
	v_add_f32_e32 v82, v94, v82
	v_add_f32_e32 v82, v95, v82
	v_add_f32_e32 v82, v96, v82
	s_waitcnt lgkmcnt(0)
	v_mfma_f32_32x32x16_bf16 v[2:17], v[90:93], v[86:89], v[2:17]
	v_add_f32_e32 v86, v97, v82
	v_exp_f32_e32 v87, v66
	v_exp_f32_e32 v88, v67
	v_exp_f32_e32 v89, v68
	v_exp_f32_e32 v90, v69
	v_exp_f32_e32 v91, v70
	v_exp_f32_e32 v92, v71
	ds_read_b64_tr_b16 v[66:67], v162 offset:18432
	ds_read_b64_tr_b16 v[68:69], v162 offset:18944
	v_exp_f32_e32 v93, v72
	v_exp_f32_e32 v94, v73
	ds_read_b64_tr_b16 v[82:83], v162 offset:22528
	ds_read_b64_tr_b16 v[84:85], v162 offset:23040
	v_cvt_pk_bf16_f32 v70, v87, v88
	v_cvt_pk_bf16_f32 v71, v89, v90
	v_cvt_pk_bf16_f32 v72, v91, v92
	v_cvt_pk_bf16_f32 v73, v93, v94
	s_waitcnt lgkmcnt(2)
	s_nop 0
	v_mfma_f32_32x32x16_bf16 v[18:33], v[66:69], v[70:73], v[18:33]
	v_add_f32_e32 v66, v87, v86
	v_add_f32_e32 v66, v88, v66
	v_add_f32_e32 v66, v89, v66
	v_add_f32_e32 v66, v90, v66
	v_add_f32_e32 v66, v91, v66
	v_add_f32_e32 v66, v92, v66
	v_add_f32_e32 v66, v93, v66
	s_waitcnt lgkmcnt(0)
	v_mfma_f32_32x32x16_bf16 v[2:17], v[82:85], v[70:73], v[2:17]
	v_add_f32_e32 v82, v94, v66
	v_exp_f32_e32 v83, v74
	v_exp_f32_e32 v84, v75
	v_exp_f32_e32 v85, v76
	v_exp_f32_e32 v86, v77
	v_exp_f32_e32 v78, v78
	v_exp_f32_e32 v79, v79
	ds_read_b64_tr_b16 v[66:67], v162 offset:19456
	ds_read_b64_tr_b16 v[68:69], v162 offset:19968
	v_exp_f32_e32 v80, v80
	v_exp_f32_e32 v81, v81
	ds_read_b64_tr_b16 v[74:75], v162 offset:23552
	ds_read_b64_tr_b16 v[76:77], v162 offset:24064
	v_cvt_pk_bf16_f32 v70, v83, v84
	v_cvt_pk_bf16_f32 v71, v85, v86
	v_cvt_pk_bf16_f32 v72, v78, v79
	v_cvt_pk_bf16_f32 v73, v80, v81
	s_waitcnt lgkmcnt(2)
	s_nop 0
	v_mfma_f32_32x32x16_bf16 v[18:33], v[66:69], v[70:73], v[18:33]
	v_add_f32_e32 v66, v83, v82
	v_add_f32_e32 v66, v84, v66
	v_add_f32_e32 v66, v85, v66
	v_add_f32_e32 v66, v86, v66
	v_add_f32_e32 v66, v78, v66
	v_add_f32_e32 v66, v79, v66
	v_add_f32_e32 v66, v80, v66
	s_waitcnt lgkmcnt(0)
	v_mfma_f32_32x32x16_bf16 v[2:17], v[74:77], v[70:73], v[2:17]
	v_add_f32_e32 v94, v81, v66
	ds_read_b128 v[82:85], v148 offset:39936
	ds_read_b128 v[86:89], v148 offset:39968
	s_waitcnt lgkmcnt(1)
	v_mfma_f32_32x32x16_bf16 v[66:81], v[82:85], v[98:101], v[34:49]
	ds_read_b128 v[82:85], v148 offset:46592
	ds_read_b128 v[90:93], v148 offset:46624
	s_waitcnt lgkmcnt(1)
	v_mfma_f32_32x32x16_bf16 v[34:49], v[82:85], v[98:101], v[34:49]
	v_mfma_f32_32x32x16_bf16 v[66:81], v[86:89], v[102:105], v[66:81]
	ds_read_b128 v[82:85], v148 offset:40000
	ds_read_b128 v[86:89], v148 offset:40032
	s_waitcnt lgkmcnt(2)
	v_mfma_f32_32x32x16_bf16 v[34:49], v[90:93], v[102:105], v[34:49]
	s_waitcnt lgkmcnt(1)
	v_mfma_f32_32x32x16_bf16 v[66:81], v[82:85], v[106:109], v[66:81]
	ds_read_b128 v[82:85], v148 offset:46656
	ds_read_b128 v[90:93], v148 offset:46688
	s_waitcnt lgkmcnt(1)
	v_mfma_f32_32x32x16_bf16 v[34:49], v[82:85], v[106:109], v[34:49]
	v_mfma_f32_32x32x16_bf16 v[66:81], v[86:89], v[110:113], v[66:81]
	ds_read_b128 v[82:85], v148 offset:40064
	ds_read_b128 v[86:89], v148 offset:40096
	s_waitcnt lgkmcnt(2)
	v_mfma_f32_32x32x16_bf16 v[34:49], v[90:93], v[110:113], v[34:49]
	s_waitcnt lgkmcnt(1)
	v_mfma_f32_32x32x16_bf16 v[66:81], v[82:85], v[114:117], v[66:81]
	ds_read_b128 v[82:85], v148 offset:46720
	ds_read_b128 v[90:93], v148 offset:46752
	s_waitcnt lgkmcnt(1)
	v_mfma_f32_32x32x16_bf16 v[34:49], v[82:85], v[114:117], v[34:49]
	v_add_f32_e32 v82, v164, v94
	v_mfma_f32_32x32x16_bf16 v[66:81], v[86:89], v[118:121], v[66:81]
	s_waitcnt lgkmcnt(0)
	v_mfma_f32_32x32x16_bf16 v[34:49], v[90:93], v[118:121], v[34:49]
	s_nop 15
	s_nop 7
	s_nop 0
	v_max3_f32 v83, v66, v67, v34
	v_max3_f32 v84, v68, v69, v35
	v_max3_f32 v83, v83, v36, v37
	v_max3_f32 v84, v84, v72, v73
	v_max3_f32 v83, v83, v70, v71
	v_max3_f32 v84, v84, v40, v41
	v_max3_f32 v83, v83, v38, v39
	v_max3_f32 v84, v84, v76, v77
	v_max3_f32 v83, v83, v74, v75
	v_max3_f32 v84, v84, v44, v45
	v_max3_f32 v83, v83, v42, v43
	v_max3_f32 v84, v84, v80, v81
	v_max3_f32 v83, v83, v78, v79
	v_max3_f32 v84, v84, v48, v49
	v_max3_f32 v83, v83, v46, v47
	v_max_f32_e32 v83, v83, v84
	v_cmp_lt_f32_e32 vcc, s59, v83
	s_cbranch_vccz .LBB0_631
; template <int DQK, int DV, bool BIAS> ...
;     ...
;         if (__any(mx > 8.f)) {
;             mx = fmaxf(mx, __shfl_xor(mx, 32));
;             const float dl = fmaxf(mx, 0.f); mhat += dl;
;             const float f = __builtin_amdgcn_exp2f(-dl);
; #pragma unroll
;             for (int r = 0; r < 16; ++r) { p0[r] -= dl; p1[r] -= dl; negm[r] = -mhat; }
;             l *= f;
; #pragma unroll
;             for (int d = 0; d < NDT; ++d)
; #pragma unroll
;                 for (int r = 0; r < 16; ++r) o[d][r] *= f;
;         }
	ds_bpermute_b32 v50, v168, v83
	s_waitcnt lgkmcnt(0)
	v_max3_f32 v52, v83, v50, 0
	v_exp_f32_e64 v54, -v52
	v_add_f32_e32 v153, v153, v52
	v_xor_b32_e32 v50, 0x80000000, v153
	v_pk_add_f32 v[66:67], v[66:67], v[52:53] op_sel_hi:[1,0] neg_lo:[0,1] neg_hi:[0,1]
	v_pk_add_f32 v[34:35], v[34:35], v[52:53] op_sel_hi:[1,0] neg_lo:[0,1] neg_hi:[0,1]
	v_pk_add_f32 v[68:69], v[68:69], v[52:53] op_sel_hi:[1,0] neg_lo:[0,1] neg_hi:[0,1]
	v_pk_add_f32 v[36:37], v[36:37], v[52:53] op_sel_hi:[1,0] neg_lo:[0,1] neg_hi:[0,1]
	v_pk_add_f32 v[70:71], v[70:71], v[52:53] op_sel_hi:[1,0] neg_lo:[0,1] neg_hi:[0,1]
	v_pk_add_f32 v[38:39], v[38:39], v[52:53] op_sel_hi:[1,0] neg_lo:[0,1] neg_hi:[0,1]
	v_pk_add_f32 v[72:73], v[72:73], v[52:53] op_sel_hi:[1,0] neg_lo:[0,1] neg_hi:[0,1]
	v_pk_add_f32 v[40:41], v[40:41], v[52:53] op_sel_hi:[1,0] neg_lo:[0,1] neg_hi:[0,1]
	v_pk_add_f32 v[74:75], v[74:75], v[52:53] op_sel_hi:[1,0] neg_lo:[0,1] neg_hi:[0,1]
	v_pk_add_f32 v[42:43], v[42:43], v[52:53] op_sel_hi:[1,0] neg_lo:[0,1] neg_hi:[0,1]
	v_pk_add_f32 v[76:77], v[76:77], v[52:53] op_sel_hi:[1,0] neg_lo:[0,1] neg_hi:[0,1]
	v_pk_add_f32 v[44:45], v[44:45], v[52:53] op_sel_hi:[1,0] neg_lo:[0,1] neg_hi:[0,1]
	v_pk_add_f32 v[78:79], v[78:79], v[52:53] op_sel_hi:[1,0] neg_lo:[0,1] neg_hi:[0,1]
	v_pk_add_f32 v[46:47], v[46:47], v[52:53] op_sel_hi:[1,0] neg_lo:[0,1] neg_hi:[0,1]
	v_pk_add_f32 v[80:81], v[80:81], v[52:53] op_sel_hi:[1,0] neg_lo:[0,1] neg_hi:[0,1]
	v_pk_add_f32 v[48:49], v[48:49], v[52:53] op_sel_hi:[1,0] neg_lo:[0,1] neg_hi:[0,1]
	v_pk_mul_f32 v[32:33], v[32:33], v[54:55] op_sel_hi:[1,0]
	v_pk_mul_f32 v[30:31], v[30:31], v[54:55] op_sel_hi:[1,0]
	v_pk_mul_f32 v[28:29], v[28:29], v[54:55] op_sel_hi:[1,0]
	v_pk_mul_f32 v[26:27], v[26:27], v[54:55] op_sel_hi:[1,0]
	v_pk_mul_f32 v[24:25], v[24:25], v[54:55] op_sel_hi:[1,0]
	v_pk_mul_f32 v[22:23], v[22:23], v[54:55] op_sel_hi:[1,0]
	v_pk_mul_f32 v[20:21], v[20:21], v[54:55] op_sel_hi:[1,0]
	v_pk_mul_f32 v[18:19], v[18:19], v[54:55] op_sel_hi:[1,0]
	v_pk_mul_f32 v[16:17], v[16:17], v[54:55] op_sel_hi:[1,0]
	v_pk_mul_f32 v[14:15], v[14:15], v[54:55] op_sel_hi:[1,0]
	v_pk_mul_f32 v[12:13], v[12:13], v[54:55] op_sel_hi:[1,0]
	v_pk_mul_f32 v[10:11], v[10:11], v[54:55] op_sel_hi:[1,0]
	v_pk_mul_f32 v[8:9], v[8:9], v[54:55] op_sel_hi:[1,0]
	v_pk_mul_f32 v[6:7], v[6:7], v[54:55] op_sel_hi:[1,0]
	v_pk_mul_f32 v[4:5], v[4:5], v[54:55] op_sel_hi:[1,0]
	v_pk_mul_f32 v[2:3], v[2:3], v[54:55] op_sel_hi:[1,0]
	v_mul_f32_e32 v82, v82, v54
	v_mov_b32_e32 v51, v50
	v_mov_b32_e32 v52, v50
	v_mov_b32_e32 v53, v50
	v_mov_b32_e32 v54, v50
	v_mov_b32_e32 v55, v50
	v_mov_b32_e32 v56, v50
	v_mov_b32_e32 v57, v50
	v_mov_b32_e32 v58, v50
	v_mov_b32_e32 v59, v50
	v_mov_b32_e32 v60, v50
	v_mov_b32_e32 v61, v50
	v_mov_b32_e32 v62, v50
	v_mov_b32_e32 v63, v50
	v_mov_b32_e32 v64, v50
	v_mov_b32_e32 v65, v50
	s_branch .LBB0_631
